# v29 + rstd fused: residual GEMM epilogue writes per-lane sum-of-squares partials (64 slots per row, no atomics), rstd phase adds the partials instead of re-reading the bf16 stream
# speedup vs baseline: 1.0086x; 1.0059x over previous
; __device__ __forceinline__ u32x4 pack8(const f32x4 a, const f32x4 b) { u32x4 w; w.x = cvt_pk_bf16(a[0], a[1]); w.y = cvt_pk_bf16(a[2], a[3]); w.z = cvt_pk_bf16(b[0], b[1]); w.w = cvt_pk_bf16(b[2], b[3]); return w; }
;     __device__ __forceinline__ void operator()(const f32x4 (&acc)[2][2][4][2], const Unit& u, int wr, int wc, int fr, int fq) const {
;         const int row0 = u.pm * BM + wr * 64 + fr, col0 = u.pn * BM + wc * 32 + 8 * fq;
; #pragma unroll
;         for (int ai = 0; ai < 2; ++ai)
; #pragma unroll
;             for (int m = 0; m < 4; ++m) { const int row = row0 + ai * HALF + m * 16; bf16_t* hp = Hx + (size_t)row * 1024;
;                 if (from_f32) { const float* xin = row < 16384 ? xa + (size_t)row * 1024 : xb + (size_t)(row - 16384) * 1024;
; #pragma unroll
;                     for (int bj = 0; bj < 2; ++bj) { const int c = col0 + bj * HALF; const f32x4 r0 = *(const f32x4*)(xin + c), r1 = *(const f32x4*)(xin + c + 4);
;                         *(u32x4*)(hp + c) = pack8(r0 + acc[ai][bj][m][0], r1 + acc[ai][bj][m][1]); }
;                 } else {
; #pragma unroll
;                     for (int bj = 0; bj < 2; ++bj) { const int c = col0 + bj * HALF; const u32x4 w = *(const u32x4*)(hp + c); f32x4 r0, r1;
;                         r0[0] = __uint_as_float(w.x << 16); r0[1] = __uint_as_float(w.x & 0xffff0000u); r0[2] = __uint_as_float(w.y << 16); r0[3] = __uint_as_float(w.y & 0xffff0000u);
;                         r1[0] = __uint_as_float(w.z << 16); r1[1] = __uint_as_float(w.z & 0xffff0000u); r1[2] = __uint_as_float(w.w << 16); r1[3] = __uint_as_float(w.w & 0xffff0000u);
;                         *(u32x4*)(hp + c) = pack8(r0 + acc[ai][bj][m][0], r1 + acc[ai][bj][m][1]); }
;                 }
;                 if (m & 1) asm volatile("" ::: "memory"); }
.LBB0_85:
	v_lshl_add_u32 v144, s13, 8, v148
	v_readlane_b32 s100, v252, 23
	v_readlane_b32 s101, v252, 24
	s_lshr_b32 vcc_lo, s33, 6
	s_and_b32 vcc_lo, vcc_lo, 3
	s_lshl_b32 vcc_lo, vcc_lo, 2
	s_lshl_b32 vcc_hi, s0, 4
	s_add_i32 vcc_lo, vcc_lo, vcc_hi
	s_mul_i32 vcc_lo, vcc_lo, 0x50000
	s_add_u32 s100, s100, vcc_lo
	s_addc_u32 s101, s101, 0
	s_add_u32 s100, s100, 0x36600000
	s_addc_u32 s101, s101, 0
	v_mbcnt_lo_u32_b32 v254, -1, 0
	v_mbcnt_hi_u32_b32 v254, -1, v254
	v_lshrrev_b32_e32 v254, 4, v254
	v_mul_u32_u24_e32 v254, 0x50000, v254
	v_lshl_add_u32 v255, v144, 2, v254
	v_ashrrev_i32_e32 v145, 31, v144
	v_lshl_or_b32 v142, s0, 8, v150
	v_lshlrev_b64 v[146:147], 11, v[144:145]
	v_cndmask_b32_e64 v0, 0, 1, s[80:81]
	v_lshl_add_u64 v[146:147], s[60:61], 0, v[146:147]
	s_mov_b64 s[4:5], -1
	v_cmp_ne_u32_e64 s[8:9], 1, v0
	s_andn2_b64 vcc, exec, s[80:81]
	v_ashrrev_i32_e32 v143, 31, v142
	s_cbranch_vccnz .LBB0_87
	v_lshl_add_u64 v[160:161], v[142:143], 1, v[146:147]
	global_load_dwordx4 v[152:155], v[160:161], off
	s_mov_b64 s[4:5], 0
	s_waitcnt vmcnt(0)
	v_lshlrev_b32_e32 v156, 16, v152
	v_and_b32_e32 v157, 0xffff0000, v152
	v_lshlrev_b32_e32 v152, 16, v153
	v_and_b32_e32 v153, 0xffff0000, v153
	v_lshlrev_b32_e32 v158, 16, v154
	v_and_b32_e32 v159, 0xffff0000, v154
	v_lshlrev_b32_e32 v154, 16, v155
	v_and_b32_e32 v155, 0xffff0000, v155
	v_pk_add_f32 v[162:163], v[128:129], v[152:153]
	v_pk_add_f32 v[152:153], v[126:127], v[156:157]
	v_pk_add_f32 v[156:157], v[124:125], v[154:155]
	v_pk_add_f32 v[154:155], v[122:123], v[158:159]
	v_cvt_pk_bf16_f32 v152, v152, v153
	v_cvt_pk_bf16_f32 v153, v162, v163
	s_nop 0
	v_cvt_pk_bf16_f32 v154, v154, v155
	v_cvt_pk_bf16_f32 v155, v156, v157
	global_load_dwordx4 v[156:159], v[160:161], off offset:256
	s_nop 0
	v_lshlrev_b32_e32 v254, 16, v152
	v_mul_f32_e32 v253, v254, v254
	v_and_b32_e32 v254, 0xffff0000, v152
	v_fmac_f32_e32 v253, v254, v254
	v_lshlrev_b32_e32 v254, 16, v153
	v_fmac_f32_e32 v253, v254, v254
	v_and_b32_e32 v254, 0xffff0000, v153
	v_fmac_f32_e32 v253, v254, v254
	v_lshlrev_b32_e32 v254, 16, v154
	v_fmac_f32_e32 v253, v254, v254
	v_and_b32_e32 v254, 0xffff0000, v154
	v_fmac_f32_e32 v253, v254, v254
	v_lshlrev_b32_e32 v254, 16, v155
	v_fmac_f32_e32 v253, v254, v254
	v_and_b32_e32 v254, 0xffff0000, v155
	v_fmac_f32_e32 v253, v254, v254
	global_store_dwordx4 v[160:161], v[152:155], off
	s_waitcnt vmcnt(1)
	s_nop 0
	v_lshlrev_b32_e32 v152, 16, v156
	v_and_b32_e32 v153, 0xffff0000, v156
	v_lshlrev_b32_e32 v154, 16, v157
	v_and_b32_e32 v155, 0xffff0000, v157
	v_lshlrev_b32_e32 v156, 16, v158
	v_and_b32_e32 v157, 0xffff0000, v158
	v_lshlrev_b32_e32 v158, 16, v159
	v_and_b32_e32 v159, 0xffff0000, v159
	v_pk_add_f32 v[154:155], v[120:121], v[154:155]
	v_pk_add_f32 v[152:153], v[118:119], v[152:153]
	v_pk_add_f32 v[158:159], v[116:117], v[158:159]
	v_pk_add_f32 v[156:157], v[114:115], v[156:157]
	v_cvt_pk_bf16_f32 v152, v152, v153
	v_cvt_pk_bf16_f32 v153, v154, v155
	s_nop 0
	v_cvt_pk_bf16_f32 v154, v156, v157
	v_cvt_pk_bf16_f32 v155, v158, v159
	v_lshlrev_b32_e32 v254, 16, v152
	v_fmac_f32_e32 v253, v254, v254
	v_and_b32_e32 v254, 0xffff0000, v152
	v_fmac_f32_e32 v253, v254, v254
	v_lshlrev_b32_e32 v254, 16, v153
	v_fmac_f32_e32 v253, v254, v254
	v_and_b32_e32 v254, 0xffff0000, v153
	v_fmac_f32_e32 v253, v254, v254
	v_lshlrev_b32_e32 v254, 16, v154
	v_fmac_f32_e32 v253, v254, v254
	v_and_b32_e32 v254, 0xffff0000, v154
	v_fmac_f32_e32 v253, v254, v254
	v_lshlrev_b32_e32 v254, 16, v155
	v_fmac_f32_e32 v253, v254, v254
	v_and_b32_e32 v254, 0xffff0000, v155
	v_fmac_f32_e32 v253, v254, v254
	global_store_dwordx4 v[160:161], v[152:155], off offset:256
	global_store_dword v255, v253, s[100:101]
.LBB0_87:
	s_andn2_b64 vcc, exec, s[4:5]
	s_cbranch_vccnz .LBB0_89
	v_add_u32_e32 v0, 0xffffc000, v144
	v_lshlrev_b64 v[152:153], 10, v[144:145]
	v_lshlrev_b64 v[154:155], 12, v[0:1]
	v_lshl_add_u64 v[152:153], v[152:153], 2, s[20:21]
	v_lshl_add_u64 v[154:155], s[22:23], 0, v[154:155]
	v_cmp_gt_i32_e32 vcc, s58, v144
	v_lshl_add_u64 v[146:147], v[142:143], 1, v[146:147]
	s_nop 0
	v_cndmask_b32_e32 v153, v155, v153, vcc
	v_cndmask_b32_e32 v152, v154, v152, vcc
	v_lshl_add_u64 v[160:161], v[142:143], 2, v[152:153]
	global_load_dwordx4 v[152:155], v[160:161], off
	global_load_dwordx4 v[156:159], v[160:161], off offset:16
	s_waitcnt vmcnt(0)
	v_pk_add_f32 v[126:127], v[126:127], v[152:153]
	v_pk_add_f32 v[152:153], v[124:125], v[158:159]
	v_pk_add_f32 v[124:125], v[122:123], v[156:157]
	v_pk_add_f32 v[128:129], v[128:129], v[154:155]
	v_cvt_pk_bf16_f32 v122, v126, v127
	s_nop 0
	v_cvt_pk_bf16_f32 v123, v128, v129
	v_cvt_pk_bf16_f32 v124, v124, v125
	v_cvt_pk_bf16_f32 v125, v152, v153
	v_lshlrev_b32_e32 v254, 16, v122
	v_mul_f32_e32 v253, v254, v254
	v_and_b32_e32 v254, 0xffff0000, v122
	v_fmac_f32_e32 v253, v254, v254
	v_lshlrev_b32_e32 v254, 16, v123
	v_fmac_f32_e32 v253, v254, v254
	v_and_b32_e32 v254, 0xffff0000, v123
	v_fmac_f32_e32 v253, v254, v254
	v_lshlrev_b32_e32 v254, 16, v124
	v_fmac_f32_e32 v253, v254, v254
	v_and_b32_e32 v254, 0xffff0000, v124
	v_fmac_f32_e32 v253, v254, v254
	v_lshlrev_b32_e32 v254, 16, v125
	v_fmac_f32_e32 v253, v254, v254
	v_and_b32_e32 v254, 0xffff0000, v125
	v_fmac_f32_e32 v253, v254, v254
	global_store_dwordx4 v[146:147], v[122:125], off
	global_load_dwordx4 v[122:125], v[160:161], off offset:512
	s_nop 0
	global_load_dwordx4 v[126:129], v[160:161], off offset:528
	s_waitcnt vmcnt(1)
	v_pk_add_f32 v[118:119], v[118:119], v[122:123]
	s_waitcnt vmcnt(0)
	v_pk_add_f32 v[122:123], v[116:117], v[128:129]
	v_pk_add_f32 v[116:117], v[114:115], v[126:127]
	v_pk_add_f32 v[120:121], v[120:121], v[124:125]
	v_cvt_pk_bf16_f32 v114, v118, v119
	s_nop 0
	v_cvt_pk_bf16_f32 v115, v120, v121
	v_cvt_pk_bf16_f32 v116, v116, v117
	v_cvt_pk_bf16_f32 v117, v122, v123
	v_lshlrev_b32_e32 v254, 16, v114
	v_fmac_f32_e32 v253, v254, v254
	v_and_b32_e32 v254, 0xffff0000, v114
	v_fmac_f32_e32 v253, v254, v254
	v_lshlrev_b32_e32 v254, 16, v115
	v_fmac_f32_e32 v253, v254, v254
	v_and_b32_e32 v254, 0xffff0000, v115
	v_fmac_f32_e32 v253, v254, v254
	v_lshlrev_b32_e32 v254, 16, v116
	v_fmac_f32_e32 v253, v254, v254
	v_and_b32_e32 v254, 0xffff0000, v116
	v_fmac_f32_e32 v253, v254, v254
	v_lshlrev_b32_e32 v254, 16, v117
	v_fmac_f32_e32 v253, v254, v254
	v_and_b32_e32 v254, 0xffff0000, v117
	v_fmac_f32_e32 v253, v254, v254
	global_store_dwordx4 v[146:147], v[114:117], off offset:256
	global_store_dword v255, v253, s[100:101]
; __device__ __forceinline__ u32x4 pack8(const f32x4 a, const f32x4 b) { u32x4 w; w.x = cvt_pk_bf16(a[0], a[1]); w.y = cvt_pk_bf16(a[2], a[3]); w.z = cvt_pk_bf16(b[0], b[1]); w.w = cvt_pk_bf16(b[2], b[3]); return w; }
;     __device__ __forceinline__ void operator()(const f32x4 (&acc)[2][2][4][2], const Unit& u, int wr, int wc, int fr, int fq) const {
;         const int row0 = u.pm * BM + wr * 64 + fr, col0 = u.pn * BM + wc * 32 + 8 * fq;
; #pragma unroll
;         for (int ai = 0; ai < 2; ++ai)
; #pragma unroll
;             for (int m = 0; m < 4; ++m) { const int row = row0 + ai * HALF + m * 16; bf16_t* hp = Hx + (size_t)row * 1024;
;                 if (from_f32) { const float* xin = row < 16384 ? xa + (size_t)row * 1024 : xb + (size_t)(row - 16384) * 1024;
; #pragma unroll
;                     for (int bj = 0; bj < 2; ++bj) { const int c = col0 + bj * HALF; const f32x4 r0 = *(const f32x4*)(xin + c), r1 = *(const f32x4*)(xin + c + 4);
;                         *(u32x4*)(hp + c) = pack8(r0 + acc[ai][bj][m][0], r1 + acc[ai][bj][m][1]); }
;                 } else {
; #pragma unroll
;                     for (int bj = 0; bj < 2; ++bj) { const int c = col0 + bj * HALF; const u32x4 w = *(const u32x4*)(hp + c); f32x4 r0, r1;
;                         r0[0] = __uint_as_float(w.x << 16); r0[1] = __uint_as_float(w.x & 0xffff0000u); r0[2] = __uint_as_float(w.y << 16); r0[3] = __uint_as_float(w.y & 0xffff0000u);
;                         r1[0] = __uint_as_float(w.z << 16); r1[1] = __uint_as_float(w.z & 0xffff0000u); r1[2] = __uint_as_float(w.w << 16); r1[3] = __uint_as_float(w.w & 0xffff0000u);
;                         *(u32x4*)(hp + c) = pack8(r0 + acc[ai][bj][m][0], r1 + acc[ai][bj][m][1]); }
;                 }
;                 if (m & 1) asm volatile("" ::: "memory"); }
.LBB0_89:
	s_nop 1
	v_or_b32_e32 v116, 16, v144
	v_ashrrev_i32_e32 v117, 31, v116
	v_lshlrev_b64 v[114:115], 11, v[116:117]
	v_lshl_add_u64 v[114:115], s[60:61], 0, v[114:115]
	s_and_b64 vcc, exec, s[8:9]
	s_mov_b64 s[4:5], -1
	s_cbranch_vccnz .LBB0_91
	v_lshl_add_u64 v[126:127], v[142:143], 1, v[114:115]
	global_load_dwordx4 v[118:121], v[126:127], off
	s_mov_b64 s[4:5], 0
	s_waitcnt vmcnt(0)
	v_lshlrev_b32_e32 v122, 16, v118
	v_and_b32_e32 v123, 0xffff0000, v118
	v_lshlrev_b32_e32 v118, 16, v119
	v_and_b32_e32 v119, 0xffff0000, v119
	v_lshlrev_b32_e32 v124, 16, v120
	v_and_b32_e32 v125, 0xffff0000, v120
	v_lshlrev_b32_e32 v120, 16, v121
	v_and_b32_e32 v121, 0xffff0000, v121
	v_pk_add_f32 v[128:129], v[112:113], v[118:119]
	v_pk_add_f32 v[118:119], v[110:111], v[122:123]
	v_pk_add_f32 v[122:123], v[108:109], v[120:121]
	v_pk_add_f32 v[120:121], v[106:107], v[124:125]
	v_cvt_pk_bf16_f32 v118, v118, v119
	v_cvt_pk_bf16_f32 v119, v128, v129
	s_nop 0
	v_cvt_pk_bf16_f32 v120, v120, v121
	v_cvt_pk_bf16_f32 v121, v122, v123
	global_load_dwordx4 v[122:125], v[126:127], off offset:256
	s_nop 0
	v_lshlrev_b32_e32 v254, 16, v118
	v_mul_f32_e32 v253, v254, v254
	v_and_b32_e32 v254, 0xffff0000, v118
	v_fmac_f32_e32 v253, v254, v254
	v_lshlrev_b32_e32 v254, 16, v119
	v_fmac_f32_e32 v253, v254, v254
	v_and_b32_e32 v254, 0xffff0000, v119
	v_fmac_f32_e32 v253, v254, v254
	v_lshlrev_b32_e32 v254, 16, v120
	v_fmac_f32_e32 v253, v254, v254
	v_and_b32_e32 v254, 0xffff0000, v120
	v_fmac_f32_e32 v253, v254, v254
	v_lshlrev_b32_e32 v254, 16, v121
	v_fmac_f32_e32 v253, v254, v254
	v_and_b32_e32 v254, 0xffff0000, v121
	v_fmac_f32_e32 v253, v254, v254
	global_store_dwordx4 v[126:127], v[118:121], off
	s_waitcnt vmcnt(1)
	s_nop 0
	v_lshlrev_b32_e32 v118, 16, v122
	v_and_b32_e32 v119, 0xffff0000, v122
	v_lshlrev_b32_e32 v120, 16, v123
	v_and_b32_e32 v121, 0xffff0000, v123
	v_lshlrev_b32_e32 v122, 16, v124
	v_and_b32_e32 v123, 0xffff0000, v124
	v_lshlrev_b32_e32 v124, 16, v125
	v_and_b32_e32 v125, 0xffff0000, v125
	v_pk_add_f32 v[120:121], v[104:105], v[120:121]
	v_pk_add_f32 v[118:119], v[102:103], v[118:119]
	v_pk_add_f32 v[124:125], v[100:101], v[124:125]
	v_pk_add_f32 v[122:123], v[98:99], v[122:123]
	v_cvt_pk_bf16_f32 v118, v118, v119
	v_cvt_pk_bf16_f32 v119, v120, v121
	s_nop 0
	v_cvt_pk_bf16_f32 v120, v122, v123
	v_cvt_pk_bf16_f32 v121, v124, v125
	v_lshlrev_b32_e32 v254, 16, v118
	v_fmac_f32_e32 v253, v254, v254
	v_and_b32_e32 v254, 0xffff0000, v118
	v_fmac_f32_e32 v253, v254, v254
	v_lshlrev_b32_e32 v254, 16, v119
	v_fmac_f32_e32 v253, v254, v254
	v_and_b32_e32 v254, 0xffff0000, v119
	v_fmac_f32_e32 v253, v254, v254
	v_lshlrev_b32_e32 v254, 16, v120
	v_fmac_f32_e32 v253, v254, v254
	v_and_b32_e32 v254, 0xffff0000, v120
	v_fmac_f32_e32 v253, v254, v254
	v_lshlrev_b32_e32 v254, 16, v121
	v_fmac_f32_e32 v253, v254, v254
	v_and_b32_e32 v254, 0xffff0000, v121
	v_fmac_f32_e32 v253, v254, v254
	global_store_dwordx4 v[126:127], v[118:121], off offset:256
	global_store_dword v255, v253, s[100:101] offset:64
.LBB0_91:
	s_andn2_b64 vcc, exec, s[4:5]
	s_cbranch_vccnz .LBB0_93
	v_add_u32_e32 v0, 0xffffc010, v144
	v_lshlrev_b64 v[118:119], 10, v[116:117]
	v_lshlrev_b64 v[120:121], 12, v[0:1]
	v_lshl_add_u64 v[118:119], v[118:119], 2, s[20:21]
	v_lshl_add_u64 v[120:121], s[22:23], 0, v[120:121]
	v_cmp_gt_i32_e32 vcc, s58, v116
	v_lshl_add_u64 v[114:115], v[142:143], 1, v[114:115]
	s_nop 0
	v_cndmask_b32_e32 v117, v121, v119, vcc
	v_cndmask_b32_e32 v116, v120, v118, vcc
	v_lshl_add_u64 v[124:125], v[142:143], 2, v[116:117]
	global_load_dwordx4 v[116:119], v[124:125], off
	global_load_dwordx4 v[120:123], v[124:125], off offset:16
	s_waitcnt vmcnt(0)
	v_pk_add_f32 v[110:111], v[110:111], v[116:117]
	v_pk_add_f32 v[116:117], v[108:109], v[122:123]
	v_pk_add_f32 v[108:109], v[106:107], v[120:121]
	v_pk_add_f32 v[112:113], v[112:113], v[118:119]
	v_cvt_pk_bf16_f32 v106, v110, v111
	s_nop 0
	v_cvt_pk_bf16_f32 v107, v112, v113
	v_cvt_pk_bf16_f32 v108, v108, v109
	v_cvt_pk_bf16_f32 v109, v116, v117
	v_lshlrev_b32_e32 v254, 16, v106
	v_mul_f32_e32 v253, v254, v254
	v_and_b32_e32 v254, 0xffff0000, v106
	v_fmac_f32_e32 v253, v254, v254
	v_lshlrev_b32_e32 v254, 16, v107
	v_fmac_f32_e32 v253, v254, v254
	v_and_b32_e32 v254, 0xffff0000, v107
	v_fmac_f32_e32 v253, v254, v254
	v_lshlrev_b32_e32 v254, 16, v108
	v_fmac_f32_e32 v253, v254, v254
	v_and_b32_e32 v254, 0xffff0000, v108
	v_fmac_f32_e32 v253, v254, v254
	v_lshlrev_b32_e32 v254, 16, v109
	v_fmac_f32_e32 v253, v254, v254
	v_and_b32_e32 v254, 0xffff0000, v109
	v_fmac_f32_e32 v253, v254, v254
	global_store_dwordx4 v[114:115], v[106:109], off
	global_load_dwordx4 v[106:109], v[124:125], off offset:512
	s_nop 0
	global_load_dwordx4 v[110:113], v[124:125], off offset:528
	s_waitcnt vmcnt(1)
	v_pk_add_f32 v[102:103], v[102:103], v[106:107]
	s_waitcnt vmcnt(0)
	v_pk_add_f32 v[106:107], v[100:101], v[112:113]
	v_pk_add_f32 v[100:101], v[98:99], v[110:111]
	v_pk_add_f32 v[104:105], v[104:105], v[108:109]
	v_cvt_pk_bf16_f32 v98, v102, v103
	s_nop 0
	v_cvt_pk_bf16_f32 v99, v104, v105
	v_cvt_pk_bf16_f32 v100, v100, v101
	v_cvt_pk_bf16_f32 v101, v106, v107
	v_lshlrev_b32_e32 v254, 16, v98
	v_fmac_f32_e32 v253, v254, v254
	v_and_b32_e32 v254, 0xffff0000, v98
	v_fmac_f32_e32 v253, v254, v254
	v_lshlrev_b32_e32 v254, 16, v99
	v_fmac_f32_e32 v253, v254, v254
	v_and_b32_e32 v254, 0xffff0000, v99
	v_fmac_f32_e32 v253, v254, v254
	v_lshlrev_b32_e32 v254, 16, v100
	v_fmac_f32_e32 v253, v254, v254
	v_and_b32_e32 v254, 0xffff0000, v100
	v_fmac_f32_e32 v253, v254, v254
	v_lshlrev_b32_e32 v254, 16, v101
	v_fmac_f32_e32 v253, v254, v254
	v_and_b32_e32 v254, 0xffff0000, v101
	v_fmac_f32_e32 v253, v254, v254
	global_store_dwordx4 v[114:115], v[98:101], off offset:256
	global_store_dword v255, v253, s[100:101] offset:64
; __device__ __forceinline__ u32x4 pack8(const f32x4 a, const f32x4 b) { u32x4 w; w.x = cvt_pk_bf16(a[0], a[1]); w.y = cvt_pk_bf16(a[2], a[3]); w.z = cvt_pk_bf16(b[0], b[1]); w.w = cvt_pk_bf16(b[2], b[3]); return w; }
;     __device__ __forceinline__ void operator()(const f32x4 (&acc)[2][2][4][2], const Unit& u, int wr, int wc, int fr, int fq) const {
;         const int row0 = u.pm * BM + wr * 64 + fr, col0 = u.pn * BM + wc * 32 + 8 * fq;
; #pragma unroll
;         for (int ai = 0; ai < 2; ++ai)
; #pragma unroll
;             for (int m = 0; m < 4; ++m) { const int row = row0 + ai * HALF + m * 16; bf16_t* hp = Hx + (size_t)row * 1024;
;                 if (from_f32) { const float* xin = row < 16384 ? xa + (size_t)row * 1024 : xb + (size_t)(row - 16384) * 1024;
; #pragma unroll
;                     for (int bj = 0; bj < 2; ++bj) { const int c = col0 + bj * HALF; const f32x4 r0 = *(const f32x4*)(xin + c), r1 = *(const f32x4*)(xin + c + 4);
;                         *(u32x4*)(hp + c) = pack8(r0 + acc[ai][bj][m][0], r1 + acc[ai][bj][m][1]); }
;                 } else {
; #pragma unroll
;                     for (int bj = 0; bj < 2; ++bj) { const int c = col0 + bj * HALF; const u32x4 w = *(const u32x4*)(hp + c); f32x4 r0, r1;
;                         r0[0] = __uint_as_float(w.x << 16); r0[1] = __uint_as_float(w.x & 0xffff0000u); r0[2] = __uint_as_float(w.y << 16); r0[3] = __uint_as_float(w.y & 0xffff0000u);
;                         r1[0] = __uint_as_float(w.z << 16); r1[1] = __uint_as_float(w.z & 0xffff0000u); r1[2] = __uint_as_float(w.w << 16); r1[3] = __uint_as_float(w.w & 0xffff0000u);
;                         *(u32x4*)(hp + c) = pack8(r0 + acc[ai][bj][m][0], r1 + acc[ai][bj][m][1]); }
;                 }
;                 if (m & 1) asm volatile("" ::: "memory"); }
.LBB0_93:
	s_nop 1
	v_or_b32_e32 v100, 32, v144
	v_ashrrev_i32_e32 v101, 31, v100
	v_lshlrev_b64 v[98:99], 11, v[100:101]
	v_lshl_add_u64 v[98:99], s[60:61], 0, v[98:99]
	s_and_b64 vcc, exec, s[8:9]
	s_mov_b64 s[4:5], -1
	s_cbranch_vccnz .LBB0_95
	v_lshl_add_u64 v[110:111], v[142:143], 1, v[98:99]
	global_load_dwordx4 v[102:105], v[110:111], off
	s_mov_b64 s[4:5], 0
	s_waitcnt vmcnt(0)
	v_lshlrev_b32_e32 v106, 16, v102
	v_and_b32_e32 v107, 0xffff0000, v102
	v_lshlrev_b32_e32 v102, 16, v103
	v_and_b32_e32 v103, 0xffff0000, v103
	v_lshlrev_b32_e32 v108, 16, v104
	v_and_b32_e32 v109, 0xffff0000, v104
	v_lshlrev_b32_e32 v104, 16, v105
	v_and_b32_e32 v105, 0xffff0000, v105
	v_pk_add_f32 v[112:113], v[96:97], v[102:103]
	v_pk_add_f32 v[102:103], v[94:95], v[106:107]
	v_pk_add_f32 v[106:107], v[92:93], v[104:105]
	v_pk_add_f32 v[104:105], v[90:91], v[108:109]
	v_cvt_pk_bf16_f32 v102, v102, v103
	v_cvt_pk_bf16_f32 v103, v112, v113
	s_nop 0
	v_cvt_pk_bf16_f32 v104, v104, v105
	v_cvt_pk_bf16_f32 v105, v106, v107
	global_load_dwordx4 v[106:109], v[110:111], off offset:256
	s_nop 0
	v_lshlrev_b32_e32 v254, 16, v102
	v_mul_f32_e32 v253, v254, v254
	v_and_b32_e32 v254, 0xffff0000, v102
	v_fmac_f32_e32 v253, v254, v254
	v_lshlrev_b32_e32 v254, 16, v103
	v_fmac_f32_e32 v253, v254, v254
	v_and_b32_e32 v254, 0xffff0000, v103
	v_fmac_f32_e32 v253, v254, v254
	v_lshlrev_b32_e32 v254, 16, v104
	v_fmac_f32_e32 v253, v254, v254
	v_and_b32_e32 v254, 0xffff0000, v104
	v_fmac_f32_e32 v253, v254, v254
	v_lshlrev_b32_e32 v254, 16, v105
	v_fmac_f32_e32 v253, v254, v254
	v_and_b32_e32 v254, 0xffff0000, v105
	v_fmac_f32_e32 v253, v254, v254
	global_store_dwordx4 v[110:111], v[102:105], off
	s_waitcnt vmcnt(1)
	s_nop 0
	v_lshlrev_b32_e32 v102, 16, v106
	v_and_b32_e32 v103, 0xffff0000, v106
	v_lshlrev_b32_e32 v104, 16, v107
	v_and_b32_e32 v105, 0xffff0000, v107
	v_lshlrev_b32_e32 v106, 16, v108
	v_and_b32_e32 v107, 0xffff0000, v108
	v_lshlrev_b32_e32 v108, 16, v109
	v_and_b32_e32 v109, 0xffff0000, v109
	v_pk_add_f32 v[104:105], v[88:89], v[104:105]
	v_pk_add_f32 v[102:103], v[86:87], v[102:103]
	v_pk_add_f32 v[108:109], v[84:85], v[108:109]
	v_pk_add_f32 v[106:107], v[82:83], v[106:107]
	v_cvt_pk_bf16_f32 v102, v102, v103
	v_cvt_pk_bf16_f32 v103, v104, v105
	s_nop 0
	v_cvt_pk_bf16_f32 v104, v106, v107
	v_cvt_pk_bf16_f32 v105, v108, v109
	v_lshlrev_b32_e32 v254, 16, v102
	v_fmac_f32_e32 v253, v254, v254
	v_and_b32_e32 v254, 0xffff0000, v102
	v_fmac_f32_e32 v253, v254, v254
	v_lshlrev_b32_e32 v254, 16, v103
	v_fmac_f32_e32 v253, v254, v254
	v_and_b32_e32 v254, 0xffff0000, v103
	v_fmac_f32_e32 v253, v254, v254
	v_lshlrev_b32_e32 v254, 16, v104
	v_fmac_f32_e32 v253, v254, v254
	v_and_b32_e32 v254, 0xffff0000, v104
	v_fmac_f32_e32 v253, v254, v254
	v_lshlrev_b32_e32 v254, 16, v105
	v_fmac_f32_e32 v253, v254, v254
	v_and_b32_e32 v254, 0xffff0000, v105
	v_fmac_f32_e32 v253, v254, v254
	global_store_dwordx4 v[110:111], v[102:105], off offset:256
	global_store_dword v255, v253, s[100:101] offset:128
.LBB0_95:
	s_andn2_b64 vcc, exec, s[4:5]
	s_cbranch_vccnz .LBB0_97
	v_add_u32_e32 v0, 0xffffc020, v144
	v_lshlrev_b64 v[102:103], 10, v[100:101]
	v_lshlrev_b64 v[104:105], 12, v[0:1]
	v_lshl_add_u64 v[102:103], v[102:103], 2, s[20:21]
	v_lshl_add_u64 v[104:105], s[22:23], 0, v[104:105]
	v_cmp_gt_i32_e32 vcc, s58, v100
	v_lshl_add_u64 v[98:99], v[142:143], 1, v[98:99]
	s_nop 0
	v_cndmask_b32_e32 v101, v105, v103, vcc
	v_cndmask_b32_e32 v100, v104, v102, vcc
	v_lshl_add_u64 v[108:109], v[142:143], 2, v[100:101]
	global_load_dwordx4 v[100:103], v[108:109], off
	global_load_dwordx4 v[104:107], v[108:109], off offset:16
	s_waitcnt vmcnt(0)
	v_pk_add_f32 v[94:95], v[94:95], v[100:101]
	v_pk_add_f32 v[100:101], v[92:93], v[106:107]
	v_pk_add_f32 v[92:93], v[90:91], v[104:105]
	v_pk_add_f32 v[96:97], v[96:97], v[102:103]
	v_cvt_pk_bf16_f32 v90, v94, v95
	s_nop 0
	v_cvt_pk_bf16_f32 v91, v96, v97
	v_cvt_pk_bf16_f32 v92, v92, v93
	v_cvt_pk_bf16_f32 v93, v100, v101
	v_lshlrev_b32_e32 v254, 16, v90
	v_mul_f32_e32 v253, v254, v254
	v_and_b32_e32 v254, 0xffff0000, v90
	v_fmac_f32_e32 v253, v254, v254
	v_lshlrev_b32_e32 v254, 16, v91
	v_fmac_f32_e32 v253, v254, v254
	v_and_b32_e32 v254, 0xffff0000, v91
	v_fmac_f32_e32 v253, v254, v254
	v_lshlrev_b32_e32 v254, 16, v92
	v_fmac_f32_e32 v253, v254, v254
	v_and_b32_e32 v254, 0xffff0000, v92
	v_fmac_f32_e32 v253, v254, v254
	v_lshlrev_b32_e32 v254, 16, v93
	v_fmac_f32_e32 v253, v254, v254
	v_and_b32_e32 v254, 0xffff0000, v93
	v_fmac_f32_e32 v253, v254, v254
	global_store_dwordx4 v[98:99], v[90:93], off
	global_load_dwordx4 v[90:93], v[108:109], off offset:512
	s_nop 0
	global_load_dwordx4 v[94:97], v[108:109], off offset:528
	s_waitcnt vmcnt(1)
	v_pk_add_f32 v[86:87], v[86:87], v[90:91]
	s_waitcnt vmcnt(0)
	v_pk_add_f32 v[90:91], v[84:85], v[96:97]
	v_pk_add_f32 v[84:85], v[82:83], v[94:95]
	v_pk_add_f32 v[88:89], v[88:89], v[92:93]
	v_cvt_pk_bf16_f32 v82, v86, v87
	s_nop 0
	v_cvt_pk_bf16_f32 v83, v88, v89
	v_cvt_pk_bf16_f32 v84, v84, v85
	v_cvt_pk_bf16_f32 v85, v90, v91
	v_lshlrev_b32_e32 v254, 16, v82
	v_fmac_f32_e32 v253, v254, v254
	v_and_b32_e32 v254, 0xffff0000, v82
	v_fmac_f32_e32 v253, v254, v254
	v_lshlrev_b32_e32 v254, 16, v83
	v_fmac_f32_e32 v253, v254, v254
	v_and_b32_e32 v254, 0xffff0000, v83
	v_fmac_f32_e32 v253, v254, v254
	v_lshlrev_b32_e32 v254, 16, v84
	v_fmac_f32_e32 v253, v254, v254
	v_and_b32_e32 v254, 0xffff0000, v84
	v_fmac_f32_e32 v253, v254, v254
	v_lshlrev_b32_e32 v254, 16, v85
	v_fmac_f32_e32 v253, v254, v254
	v_and_b32_e32 v254, 0xffff0000, v85
	v_fmac_f32_e32 v253, v254, v254
	global_store_dwordx4 v[98:99], v[82:85], off offset:256
	global_store_dword v255, v253, s[100:101] offset:128
; __device__ __forceinline__ u32x4 pack8(const f32x4 a, const f32x4 b) { u32x4 w; w.x = cvt_pk_bf16(a[0], a[1]); w.y = cvt_pk_bf16(a[2], a[3]); w.z = cvt_pk_bf16(b[0], b[1]); w.w = cvt_pk_bf16(b[2], b[3]); return w; }
;     __device__ __forceinline__ void operator()(const f32x4 (&acc)[2][2][4][2], const Unit& u, int wr, int wc, int fr, int fq) const {
;         const int row0 = u.pm * BM + wr * 64 + fr, col0 = u.pn * BM + wc * 32 + 8 * fq;
; #pragma unroll
;         for (int ai = 0; ai < 2; ++ai)
; #pragma unroll
;             for (int m = 0; m < 4; ++m) { const int row = row0 + ai * HALF + m * 16; bf16_t* hp = Hx + (size_t)row * 1024;
;                 if (from_f32) { const float* xin = row < 16384 ? xa + (size_t)row * 1024 : xb + (size_t)(row - 16384) * 1024;
; #pragma unroll
;                     for (int bj = 0; bj < 2; ++bj) { const int c = col0 + bj * HALF; const f32x4 r0 = *(const f32x4*)(xin + c), r1 = *(const f32x4*)(xin + c + 4);
;                         *(u32x4*)(hp + c) = pack8(r0 + acc[ai][bj][m][0], r1 + acc[ai][bj][m][1]); }
;                 } else {
; #pragma unroll
;                     for (int bj = 0; bj < 2; ++bj) { const int c = col0 + bj * HALF; const u32x4 w = *(const u32x4*)(hp + c); f32x4 r0, r1;
;                         r0[0] = __uint_as_float(w.x << 16); r0[1] = __uint_as_float(w.x & 0xffff0000u); r0[2] = __uint_as_float(w.y << 16); r0[3] = __uint_as_float(w.y & 0xffff0000u);
;                         r1[0] = __uint_as_float(w.z << 16); r1[1] = __uint_as_float(w.z & 0xffff0000u); r1[2] = __uint_as_float(w.w << 16); r1[3] = __uint_as_float(w.w & 0xffff0000u);
;                         *(u32x4*)(hp + c) = pack8(r0 + acc[ai][bj][m][0], r1 + acc[ai][bj][m][1]); }
;                 }
;                 if (m & 1) asm volatile("" ::: "memory"); }
.LBB0_97:
	s_nop 1
	v_or_b32_e32 v84, 48, v144
	v_ashrrev_i32_e32 v85, 31, v84
	v_lshlrev_b64 v[82:83], 11, v[84:85]
	v_lshl_add_u64 v[82:83], s[60:61], 0, v[82:83]
	s_and_b64 vcc, exec, s[8:9]
	s_mov_b64 s[4:5], -1
	s_cbranch_vccnz .LBB0_99
	v_lshl_add_u64 v[94:95], v[142:143], 1, v[82:83]
	global_load_dwordx4 v[86:89], v[94:95], off
	s_mov_b64 s[4:5], 0
	s_waitcnt vmcnt(0)
	v_lshlrev_b32_e32 v90, 16, v86
	v_and_b32_e32 v91, 0xffff0000, v86
	v_lshlrev_b32_e32 v86, 16, v87
	v_and_b32_e32 v87, 0xffff0000, v87
	v_lshlrev_b32_e32 v92, 16, v88
	v_and_b32_e32 v93, 0xffff0000, v88
	v_lshlrev_b32_e32 v88, 16, v89
	v_and_b32_e32 v89, 0xffff0000, v89
	v_pk_add_f32 v[96:97], v[80:81], v[86:87]
	v_pk_add_f32 v[86:87], v[78:79], v[90:91]
	v_pk_add_f32 v[90:91], v[76:77], v[88:89]
	v_pk_add_f32 v[88:89], v[74:75], v[92:93]
	v_cvt_pk_bf16_f32 v86, v86, v87
	v_cvt_pk_bf16_f32 v87, v96, v97
	s_nop 0
	v_cvt_pk_bf16_f32 v88, v88, v89
	v_cvt_pk_bf16_f32 v89, v90, v91
	global_load_dwordx4 v[90:93], v[94:95], off offset:256
	s_nop 0
	v_lshlrev_b32_e32 v254, 16, v86
	v_mul_f32_e32 v253, v254, v254
	v_and_b32_e32 v254, 0xffff0000, v86
	v_fmac_f32_e32 v253, v254, v254
	v_lshlrev_b32_e32 v254, 16, v87
	v_fmac_f32_e32 v253, v254, v254
	v_and_b32_e32 v254, 0xffff0000, v87
	v_fmac_f32_e32 v253, v254, v254
	v_lshlrev_b32_e32 v254, 16, v88
	v_fmac_f32_e32 v253, v254, v254
	v_and_b32_e32 v254, 0xffff0000, v88
	v_fmac_f32_e32 v253, v254, v254
	v_lshlrev_b32_e32 v254, 16, v89
	v_fmac_f32_e32 v253, v254, v254
	v_and_b32_e32 v254, 0xffff0000, v89
	v_fmac_f32_e32 v253, v254, v254
	global_store_dwordx4 v[94:95], v[86:89], off
	s_waitcnt vmcnt(1)
	s_nop 0
	v_lshlrev_b32_e32 v86, 16, v90
	v_and_b32_e32 v87, 0xffff0000, v90
	v_lshlrev_b32_e32 v88, 16, v91
	v_and_b32_e32 v89, 0xffff0000, v91
	v_lshlrev_b32_e32 v90, 16, v92
	v_and_b32_e32 v91, 0xffff0000, v92
	v_lshlrev_b32_e32 v92, 16, v93
	v_and_b32_e32 v93, 0xffff0000, v93
	v_pk_add_f32 v[88:89], v[72:73], v[88:89]
	v_pk_add_f32 v[86:87], v[70:71], v[86:87]
	v_pk_add_f32 v[92:93], v[68:69], v[92:93]
	v_pk_add_f32 v[90:91], v[66:67], v[90:91]
	v_cvt_pk_bf16_f32 v86, v86, v87
	v_cvt_pk_bf16_f32 v87, v88, v89
	s_nop 0
	v_cvt_pk_bf16_f32 v88, v90, v91
	v_cvt_pk_bf16_f32 v89, v92, v93
	v_lshlrev_b32_e32 v254, 16, v86
	v_fmac_f32_e32 v253, v254, v254
	v_and_b32_e32 v254, 0xffff0000, v86
	v_fmac_f32_e32 v253, v254, v254
	v_lshlrev_b32_e32 v254, 16, v87
	v_fmac_f32_e32 v253, v254, v254
	v_and_b32_e32 v254, 0xffff0000, v87
	v_fmac_f32_e32 v253, v254, v254
	v_lshlrev_b32_e32 v254, 16, v88
	v_fmac_f32_e32 v253, v254, v254
	v_and_b32_e32 v254, 0xffff0000, v88
	v_fmac_f32_e32 v253, v254, v254
	v_lshlrev_b32_e32 v254, 16, v89
	v_fmac_f32_e32 v253, v254, v254
	v_and_b32_e32 v254, 0xffff0000, v89
	v_fmac_f32_e32 v253, v254, v254
	global_store_dwordx4 v[94:95], v[86:89], off offset:256
	global_store_dword v255, v253, s[100:101] offset:192
.LBB0_99:
	s_andn2_b64 vcc, exec, s[4:5]
	s_cbranch_vccnz .LBB0_101
	v_add_u32_e32 v0, 0xffffc030, v144
	v_lshlrev_b64 v[86:87], 10, v[84:85]
	v_lshlrev_b64 v[88:89], 12, v[0:1]
	v_lshl_add_u64 v[86:87], v[86:87], 2, s[20:21]
	v_lshl_add_u64 v[88:89], s[22:23], 0, v[88:89]
	v_cmp_gt_i32_e32 vcc, s58, v84
	v_lshl_add_u64 v[82:83], v[142:143], 1, v[82:83]
	s_nop 0
	v_cndmask_b32_e32 v85, v89, v87, vcc
	v_cndmask_b32_e32 v84, v88, v86, vcc
	v_lshl_add_u64 v[92:93], v[142:143], 2, v[84:85]
	global_load_dwordx4 v[84:87], v[92:93], off
	global_load_dwordx4 v[88:91], v[92:93], off offset:16
	s_waitcnt vmcnt(0)
	v_pk_add_f32 v[78:79], v[78:79], v[84:85]
	v_pk_add_f32 v[84:85], v[76:77], v[90:91]
	v_pk_add_f32 v[76:77], v[74:75], v[88:89]
	v_pk_add_f32 v[80:81], v[80:81], v[86:87]
	v_cvt_pk_bf16_f32 v74, v78, v79
	s_nop 0
	v_cvt_pk_bf16_f32 v75, v80, v81
	v_cvt_pk_bf16_f32 v76, v76, v77
	v_cvt_pk_bf16_f32 v77, v84, v85
	v_lshlrev_b32_e32 v254, 16, v74
	v_mul_f32_e32 v253, v254, v254
	v_and_b32_e32 v254, 0xffff0000, v74
	v_fmac_f32_e32 v253, v254, v254
	v_lshlrev_b32_e32 v254, 16, v75
	v_fmac_f32_e32 v253, v254, v254
	v_and_b32_e32 v254, 0xffff0000, v75
	v_fmac_f32_e32 v253, v254, v254
	v_lshlrev_b32_e32 v254, 16, v76
	v_fmac_f32_e32 v253, v254, v254
	v_and_b32_e32 v254, 0xffff0000, v76
	v_fmac_f32_e32 v253, v254, v254
	v_lshlrev_b32_e32 v254, 16, v77
	v_fmac_f32_e32 v253, v254, v254
	v_and_b32_e32 v254, 0xffff0000, v77
	v_fmac_f32_e32 v253, v254, v254
	global_store_dwordx4 v[82:83], v[74:77], off
	global_load_dwordx4 v[74:77], v[92:93], off offset:512
	s_nop 0
	global_load_dwordx4 v[78:81], v[92:93], off offset:528
	s_waitcnt vmcnt(1)
	v_pk_add_f32 v[70:71], v[70:71], v[74:75]
	s_waitcnt vmcnt(0)
	v_pk_add_f32 v[74:75], v[68:69], v[80:81]
	v_pk_add_f32 v[68:69], v[66:67], v[78:79]
	v_pk_add_f32 v[72:73], v[72:73], v[76:77]
	v_cvt_pk_bf16_f32 v66, v70, v71
	s_nop 0
	v_cvt_pk_bf16_f32 v67, v72, v73
	v_cvt_pk_bf16_f32 v68, v68, v69
	v_cvt_pk_bf16_f32 v69, v74, v75
	v_lshlrev_b32_e32 v254, 16, v66
	v_fmac_f32_e32 v253, v254, v254
	v_and_b32_e32 v254, 0xffff0000, v66
	v_fmac_f32_e32 v253, v254, v254
	v_lshlrev_b32_e32 v254, 16, v67
	v_fmac_f32_e32 v253, v254, v254
	v_and_b32_e32 v254, 0xffff0000, v67
	v_fmac_f32_e32 v253, v254, v254
	v_lshlrev_b32_e32 v254, 16, v68
	v_fmac_f32_e32 v253, v254, v254
	v_and_b32_e32 v254, 0xffff0000, v68
	v_fmac_f32_e32 v253, v254, v254
	v_lshlrev_b32_e32 v254, 16, v69
	v_fmac_f32_e32 v253, v254, v254
	v_and_b32_e32 v254, 0xffff0000, v69
	v_fmac_f32_e32 v253, v254, v254
	global_store_dwordx4 v[82:83], v[66:69], off offset:256
	global_store_dword v255, v253, s[100:101] offset:192
; __device__ __forceinline__ u32x4 pack8(const f32x4 a, const f32x4 b) { u32x4 w; w.x = cvt_pk_bf16(a[0], a[1]); w.y = cvt_pk_bf16(a[2], a[3]); w.z = cvt_pk_bf16(b[0], b[1]); w.w = cvt_pk_bf16(b[2], b[3]); return w; }
;     __device__ __forceinline__ void operator()(const f32x4 (&acc)[2][2][4][2], const Unit& u, int wr, int wc, int fr, int fq) const {
;         const int row0 = u.pm * BM + wr * 64 + fr, col0 = u.pn * BM + wc * 32 + 8 * fq;
; #pragma unroll
;         for (int ai = 0; ai < 2; ++ai)
; #pragma unroll
;             for (int m = 0; m < 4; ++m) { const int row = row0 + ai * HALF + m * 16; bf16_t* hp = Hx + (size_t)row * 1024;
;                 if (from_f32) { const float* xin = row < 16384 ? xa + (size_t)row * 1024 : xb + (size_t)(row - 16384) * 1024;
; #pragma unroll
;                     for (int bj = 0; bj < 2; ++bj) { const int c = col0 + bj * HALF; const f32x4 r0 = *(const f32x4*)(xin + c), r1 = *(const f32x4*)(xin + c + 4);
;                         *(u32x4*)(hp + c) = pack8(r0 + acc[ai][bj][m][0], r1 + acc[ai][bj][m][1]); }
;                 } else {
; #pragma unroll
;                     for (int bj = 0; bj < 2; ++bj) { const int c = col0 + bj * HALF; const u32x4 w = *(const u32x4*)(hp + c); f32x4 r0, r1;
;                         r0[0] = __uint_as_float(w.x << 16); r0[1] = __uint_as_float(w.x & 0xffff0000u); r0[2] = __uint_as_float(w.y << 16); r0[3] = __uint_as_float(w.y & 0xffff0000u);
;                         r1[0] = __uint_as_float(w.z << 16); r1[1] = __uint_as_float(w.z & 0xffff0000u); r1[2] = __uint_as_float(w.w << 16); r1[3] = __uint_as_float(w.w & 0xffff0000u);
;                         *(u32x4*)(hp + c) = pack8(r0 + acc[ai][bj][m][0], r1 + acc[ai][bj][m][1]); }
;                 }
;                 if (m & 1) asm volatile("" ::: "memory"); }
.LBB0_101:
	s_nop 1
	v_add_u32_e32 v68, 0x80, v144
	v_ashrrev_i32_e32 v69, 31, v68
	v_lshlrev_b64 v[66:67], 11, v[68:69]
	v_lshl_add_u64 v[66:67], s[60:61], 0, v[66:67]
	s_and_b64 vcc, exec, s[8:9]
	s_mov_b64 s[4:5], -1
	s_cbranch_vccnz .LBB0_103
	v_lshl_add_u64 v[78:79], v[142:143], 1, v[66:67]
	global_load_dwordx4 v[70:73], v[78:79], off
	s_mov_b64 s[4:5], 0
	s_waitcnt vmcnt(0)
	v_lshlrev_b32_e32 v74, 16, v70
	v_and_b32_e32 v75, 0xffff0000, v70
	v_lshlrev_b32_e32 v70, 16, v71
	v_and_b32_e32 v71, 0xffff0000, v71
	v_lshlrev_b32_e32 v76, 16, v72
	v_and_b32_e32 v77, 0xffff0000, v72
	v_lshlrev_b32_e32 v72, 16, v73
	v_and_b32_e32 v73, 0xffff0000, v73
	v_pk_add_f32 v[80:81], v[64:65], v[70:71]
	v_pk_add_f32 v[70:71], v[62:63], v[74:75]
	v_pk_add_f32 v[74:75], v[60:61], v[72:73]
	v_pk_add_f32 v[72:73], v[58:59], v[76:77]
	v_cvt_pk_bf16_f32 v70, v70, v71
	v_cvt_pk_bf16_f32 v71, v80, v81
	s_nop 0
	v_cvt_pk_bf16_f32 v72, v72, v73
	v_cvt_pk_bf16_f32 v73, v74, v75
	global_load_dwordx4 v[74:77], v[78:79], off offset:256
	s_nop 0
	v_lshlrev_b32_e32 v254, 16, v70
	v_mul_f32_e32 v253, v254, v254
	v_and_b32_e32 v254, 0xffff0000, v70
	v_fmac_f32_e32 v253, v254, v254
	v_lshlrev_b32_e32 v254, 16, v71
	v_fmac_f32_e32 v253, v254, v254
	v_and_b32_e32 v254, 0xffff0000, v71
	v_fmac_f32_e32 v253, v254, v254
	v_lshlrev_b32_e32 v254, 16, v72
	v_fmac_f32_e32 v253, v254, v254
	v_and_b32_e32 v254, 0xffff0000, v72
	v_fmac_f32_e32 v253, v254, v254
	v_lshlrev_b32_e32 v254, 16, v73
	v_fmac_f32_e32 v253, v254, v254
	v_and_b32_e32 v254, 0xffff0000, v73
	v_fmac_f32_e32 v253, v254, v254
	global_store_dwordx4 v[78:79], v[70:73], off
	s_waitcnt vmcnt(1)
	s_nop 0
	v_lshlrev_b32_e32 v70, 16, v74
	v_and_b32_e32 v71, 0xffff0000, v74
	v_lshlrev_b32_e32 v72, 16, v75
	v_and_b32_e32 v73, 0xffff0000, v75
	v_lshlrev_b32_e32 v74, 16, v76
	v_and_b32_e32 v75, 0xffff0000, v76
	v_lshlrev_b32_e32 v76, 16, v77
	v_and_b32_e32 v77, 0xffff0000, v77
	v_pk_add_f32 v[72:73], v[56:57], v[72:73]
	v_pk_add_f32 v[70:71], v[54:55], v[70:71]
	v_pk_add_f32 v[76:77], v[52:53], v[76:77]
	v_pk_add_f32 v[74:75], v[50:51], v[74:75]
	v_cvt_pk_bf16_f32 v70, v70, v71
	v_cvt_pk_bf16_f32 v71, v72, v73
	s_nop 0
	v_cvt_pk_bf16_f32 v72, v74, v75
	v_cvt_pk_bf16_f32 v73, v76, v77
	v_lshlrev_b32_e32 v254, 16, v70
	v_fmac_f32_e32 v253, v254, v254
	v_and_b32_e32 v254, 0xffff0000, v70
	v_fmac_f32_e32 v253, v254, v254
	v_lshlrev_b32_e32 v254, 16, v71
	v_fmac_f32_e32 v253, v254, v254
	v_and_b32_e32 v254, 0xffff0000, v71
	v_fmac_f32_e32 v253, v254, v254
	v_lshlrev_b32_e32 v254, 16, v72
	v_fmac_f32_e32 v253, v254, v254
	v_and_b32_e32 v254, 0xffff0000, v72
	v_fmac_f32_e32 v253, v254, v254
	v_lshlrev_b32_e32 v254, 16, v73
	v_fmac_f32_e32 v253, v254, v254
	v_and_b32_e32 v254, 0xffff0000, v73
	v_fmac_f32_e32 v253, v254, v254
	global_store_dwordx4 v[78:79], v[70:73], off offset:256
	global_store_dword v255, v253, s[100:101] offset:512
.LBB0_103:
	s_andn2_b64 vcc, exec, s[4:5]
	s_cbranch_vccnz .LBB0_105
	v_add_u32_e32 v0, 0xffffc080, v144
	v_lshlrev_b64 v[68:69], 10, v[68:69]
	v_lshlrev_b64 v[70:71], 12, v[0:1]
	s_movk_i32 s0, 0x3f80
	v_lshl_add_u64 v[68:69], v[68:69], 2, s[20:21]
	v_lshl_add_u64 v[70:71], s[22:23], 0, v[70:71]
	v_cmp_gt_i32_e32 vcc, s0, v144
	v_lshl_add_u64 v[66:67], v[142:143], 1, v[66:67]
	s_nop 0
	v_cndmask_b32_e32 v69, v71, v69, vcc
	v_cndmask_b32_e32 v68, v70, v68, vcc
	v_lshl_add_u64 v[76:77], v[142:143], 2, v[68:69]
	global_load_dwordx4 v[68:71], v[76:77], off
	global_load_dwordx4 v[72:75], v[76:77], off offset:16
	s_waitcnt vmcnt(0)
	v_pk_add_f32 v[62:63], v[62:63], v[68:69]
	v_pk_add_f32 v[68:69], v[60:61], v[74:75]
	v_pk_add_f32 v[60:61], v[58:59], v[72:73]
	v_pk_add_f32 v[64:65], v[64:65], v[70:71]
	v_cvt_pk_bf16_f32 v58, v62, v63
	s_nop 0
	v_cvt_pk_bf16_f32 v59, v64, v65
	v_cvt_pk_bf16_f32 v60, v60, v61
	v_cvt_pk_bf16_f32 v61, v68, v69
	v_lshlrev_b32_e32 v254, 16, v58
	v_mul_f32_e32 v253, v254, v254
	v_and_b32_e32 v254, 0xffff0000, v58
	v_fmac_f32_e32 v253, v254, v254
	v_lshlrev_b32_e32 v254, 16, v59
	v_fmac_f32_e32 v253, v254, v254
	v_and_b32_e32 v254, 0xffff0000, v59
	v_fmac_f32_e32 v253, v254, v254
	v_lshlrev_b32_e32 v254, 16, v60
	v_fmac_f32_e32 v253, v254, v254
	v_and_b32_e32 v254, 0xffff0000, v60
	v_fmac_f32_e32 v253, v254, v254
	v_lshlrev_b32_e32 v254, 16, v61
	v_fmac_f32_e32 v253, v254, v254
	v_and_b32_e32 v254, 0xffff0000, v61
	v_fmac_f32_e32 v253, v254, v254
	global_store_dwordx4 v[66:67], v[58:61], off
	global_load_dwordx4 v[58:61], v[76:77], off offset:512
	s_nop 0
	global_load_dwordx4 v[62:65], v[76:77], off offset:528
	s_waitcnt vmcnt(1)
	v_pk_add_f32 v[54:55], v[54:55], v[58:59]
	s_waitcnt vmcnt(0)
	v_pk_add_f32 v[58:59], v[52:53], v[64:65]
	v_pk_add_f32 v[52:53], v[50:51], v[62:63]
	v_pk_add_f32 v[56:57], v[56:57], v[60:61]
	v_cvt_pk_bf16_f32 v50, v54, v55
	s_nop 0
	v_cvt_pk_bf16_f32 v51, v56, v57
	v_cvt_pk_bf16_f32 v52, v52, v53
	v_cvt_pk_bf16_f32 v53, v58, v59
	v_lshlrev_b32_e32 v254, 16, v50
	v_fmac_f32_e32 v253, v254, v254
	v_and_b32_e32 v254, 0xffff0000, v50
	v_fmac_f32_e32 v253, v254, v254
	v_lshlrev_b32_e32 v254, 16, v51
	v_fmac_f32_e32 v253, v254, v254
	v_and_b32_e32 v254, 0xffff0000, v51
	v_fmac_f32_e32 v253, v254, v254
	v_lshlrev_b32_e32 v254, 16, v52
	v_fmac_f32_e32 v253, v254, v254
	v_and_b32_e32 v254, 0xffff0000, v52
	v_fmac_f32_e32 v253, v254, v254
	v_lshlrev_b32_e32 v254, 16, v53
	v_fmac_f32_e32 v253, v254, v254
	v_and_b32_e32 v254, 0xffff0000, v53
	v_fmac_f32_e32 v253, v254, v254
	global_store_dwordx4 v[66:67], v[50:53], off offset:256
	global_store_dword v255, v253, s[100:101] offset:512
; __device__ __forceinline__ u32x4 pack8(const f32x4 a, const f32x4 b) { u32x4 w; w.x = cvt_pk_bf16(a[0], a[1]); w.y = cvt_pk_bf16(a[2], a[3]); w.z = cvt_pk_bf16(b[0], b[1]); w.w = cvt_pk_bf16(b[2], b[3]); return w; }
;     __device__ __forceinline__ void operator()(const f32x4 (&acc)[2][2][4][2], const Unit& u, int wr, int wc, int fr, int fq) const {
;         const int row0 = u.pm * BM + wr * 64 + fr, col0 = u.pn * BM + wc * 32 + 8 * fq;
; #pragma unroll
;         for (int ai = 0; ai < 2; ++ai)
; #pragma unroll
;             for (int m = 0; m < 4; ++m) { const int row = row0 + ai * HALF + m * 16; bf16_t* hp = Hx + (size_t)row * 1024;
;                 if (from_f32) { const float* xin = row < 16384 ? xa + (size_t)row * 1024 : xb + (size_t)(row - 16384) * 1024;
; #pragma unroll
;                     for (int bj = 0; bj < 2; ++bj) { const int c = col0 + bj * HALF; const f32x4 r0 = *(const f32x4*)(xin + c), r1 = *(const f32x4*)(xin + c + 4);
;                         *(u32x4*)(hp + c) = pack8(r0 + acc[ai][bj][m][0], r1 + acc[ai][bj][m][1]); }
;                 } else {
; #pragma unroll
;                     for (int bj = 0; bj < 2; ++bj) { const int c = col0 + bj * HALF; const u32x4 w = *(const u32x4*)(hp + c); f32x4 r0, r1;
;                         r0[0] = __uint_as_float(w.x << 16); r0[1] = __uint_as_float(w.x & 0xffff0000u); r0[2] = __uint_as_float(w.y << 16); r0[3] = __uint_as_float(w.y & 0xffff0000u);
;                         r1[0] = __uint_as_float(w.z << 16); r1[1] = __uint_as_float(w.z & 0xffff0000u); r1[2] = __uint_as_float(w.w << 16); r1[3] = __uint_as_float(w.w & 0xffff0000u);
;                         *(u32x4*)(hp + c) = pack8(r0 + acc[ai][bj][m][0], r1 + acc[ai][bj][m][1]); }
;                 }
;                 if (m & 1) asm volatile("" ::: "memory"); }
.LBB0_105:
	s_nop 1
	v_add_u32_e32 v52, 0x90, v144
	v_ashrrev_i32_e32 v53, 31, v52
	v_lshlrev_b64 v[50:51], 11, v[52:53]
	v_lshl_add_u64 v[50:51], s[60:61], 0, v[50:51]
	s_and_b64 vcc, exec, s[8:9]
	s_mov_b64 s[4:5], -1
	s_cbranch_vccnz .LBB0_107
	v_lshl_add_u64 v[62:63], v[142:143], 1, v[50:51]
	global_load_dwordx4 v[54:57], v[62:63], off
	s_mov_b64 s[4:5], 0
	s_waitcnt vmcnt(0)
	v_lshlrev_b32_e32 v58, 16, v54
	v_and_b32_e32 v59, 0xffff0000, v54
	v_lshlrev_b32_e32 v54, 16, v55
	v_and_b32_e32 v55, 0xffff0000, v55
	v_lshlrev_b32_e32 v60, 16, v56
	v_and_b32_e32 v61, 0xffff0000, v56
	v_lshlrev_b32_e32 v56, 16, v57
	v_and_b32_e32 v57, 0xffff0000, v57
	v_pk_add_f32 v[64:65], v[48:49], v[54:55]
	v_pk_add_f32 v[54:55], v[46:47], v[58:59]
	v_pk_add_f32 v[58:59], v[44:45], v[56:57]
	v_pk_add_f32 v[56:57], v[42:43], v[60:61]
	v_cvt_pk_bf16_f32 v54, v54, v55
	v_cvt_pk_bf16_f32 v55, v64, v65
	s_nop 0
	v_cvt_pk_bf16_f32 v56, v56, v57
	v_cvt_pk_bf16_f32 v57, v58, v59
	global_load_dwordx4 v[58:61], v[62:63], off offset:256
	s_nop 0
	v_lshlrev_b32_e32 v254, 16, v54
	v_mul_f32_e32 v253, v254, v254
	v_and_b32_e32 v254, 0xffff0000, v54
	v_fmac_f32_e32 v253, v254, v254
	v_lshlrev_b32_e32 v254, 16, v55
	v_fmac_f32_e32 v253, v254, v254
	v_and_b32_e32 v254, 0xffff0000, v55
	v_fmac_f32_e32 v253, v254, v254
	v_lshlrev_b32_e32 v254, 16, v56
	v_fmac_f32_e32 v253, v254, v254
	v_and_b32_e32 v254, 0xffff0000, v56
	v_fmac_f32_e32 v253, v254, v254
	v_lshlrev_b32_e32 v254, 16, v57
	v_fmac_f32_e32 v253, v254, v254
	v_and_b32_e32 v254, 0xffff0000, v57
	v_fmac_f32_e32 v253, v254, v254
	global_store_dwordx4 v[62:63], v[54:57], off
	s_waitcnt vmcnt(1)
	s_nop 0
	v_lshlrev_b32_e32 v54, 16, v58
	v_and_b32_e32 v55, 0xffff0000, v58
	v_lshlrev_b32_e32 v56, 16, v59
	v_and_b32_e32 v57, 0xffff0000, v59
	v_lshlrev_b32_e32 v58, 16, v60
	v_and_b32_e32 v59, 0xffff0000, v60
	v_lshlrev_b32_e32 v60, 16, v61
	v_and_b32_e32 v61, 0xffff0000, v61
	v_pk_add_f32 v[56:57], v[40:41], v[56:57]
	v_pk_add_f32 v[54:55], v[38:39], v[54:55]
	v_pk_add_f32 v[60:61], v[36:37], v[60:61]
	v_pk_add_f32 v[58:59], v[34:35], v[58:59]
	v_cvt_pk_bf16_f32 v54, v54, v55
	v_cvt_pk_bf16_f32 v55, v56, v57
	s_nop 0
	v_cvt_pk_bf16_f32 v56, v58, v59
	v_cvt_pk_bf16_f32 v57, v60, v61
	v_lshlrev_b32_e32 v254, 16, v54
	v_fmac_f32_e32 v253, v254, v254
	v_and_b32_e32 v254, 0xffff0000, v54
	v_fmac_f32_e32 v253, v254, v254
	v_lshlrev_b32_e32 v254, 16, v55
	v_fmac_f32_e32 v253, v254, v254
	v_and_b32_e32 v254, 0xffff0000, v55
	v_fmac_f32_e32 v253, v254, v254
	v_lshlrev_b32_e32 v254, 16, v56
	v_fmac_f32_e32 v253, v254, v254
	v_and_b32_e32 v254, 0xffff0000, v56
	v_fmac_f32_e32 v253, v254, v254
	v_lshlrev_b32_e32 v254, 16, v57
	v_fmac_f32_e32 v253, v254, v254
	v_and_b32_e32 v254, 0xffff0000, v57
	v_fmac_f32_e32 v253, v254, v254
	global_store_dwordx4 v[62:63], v[54:57], off offset:256
	global_store_dword v255, v253, s[100:101] offset:576
.LBB0_107:
	s_andn2_b64 vcc, exec, s[4:5]
	s_cbranch_vccnz .LBB0_109
	v_add_u32_e32 v0, 0xffffc090, v144
	v_lshlrev_b64 v[52:53], 10, v[52:53]
	v_lshlrev_b64 v[54:55], 12, v[0:1]
	s_movk_i32 s0, 0x3f70
	v_lshl_add_u64 v[52:53], v[52:53], 2, s[20:21]
	v_lshl_add_u64 v[54:55], s[22:23], 0, v[54:55]
	v_cmp_gt_i32_e32 vcc, s0, v144
	v_lshl_add_u64 v[50:51], v[142:143], 1, v[50:51]
	s_nop 0
	v_cndmask_b32_e32 v53, v55, v53, vcc
	v_cndmask_b32_e32 v52, v54, v52, vcc
	v_lshl_add_u64 v[60:61], v[142:143], 2, v[52:53]
	global_load_dwordx4 v[52:55], v[60:61], off
	global_load_dwordx4 v[56:59], v[60:61], off offset:16
	s_waitcnt vmcnt(0)
	v_pk_add_f32 v[46:47], v[46:47], v[52:53]
	v_pk_add_f32 v[52:53], v[44:45], v[58:59]
	v_pk_add_f32 v[44:45], v[42:43], v[56:57]
	v_pk_add_f32 v[48:49], v[48:49], v[54:55]
	v_cvt_pk_bf16_f32 v42, v46, v47
	s_nop 0
	v_cvt_pk_bf16_f32 v43, v48, v49
	v_cvt_pk_bf16_f32 v44, v44, v45
	v_cvt_pk_bf16_f32 v45, v52, v53
	v_lshlrev_b32_e32 v254, 16, v42
	v_mul_f32_e32 v253, v254, v254
	v_and_b32_e32 v254, 0xffff0000, v42
	v_fmac_f32_e32 v253, v254, v254
	v_lshlrev_b32_e32 v254, 16, v43
	v_fmac_f32_e32 v253, v254, v254
	v_and_b32_e32 v254, 0xffff0000, v43
	v_fmac_f32_e32 v253, v254, v254
	v_lshlrev_b32_e32 v254, 16, v44
	v_fmac_f32_e32 v253, v254, v254
	v_and_b32_e32 v254, 0xffff0000, v44
	v_fmac_f32_e32 v253, v254, v254
	v_lshlrev_b32_e32 v254, 16, v45
	v_fmac_f32_e32 v253, v254, v254
	v_and_b32_e32 v254, 0xffff0000, v45
	v_fmac_f32_e32 v253, v254, v254
	global_store_dwordx4 v[50:51], v[42:45], off
	global_load_dwordx4 v[42:45], v[60:61], off offset:512
	s_nop 0
	global_load_dwordx4 v[46:49], v[60:61], off offset:528
	s_waitcnt vmcnt(1)
	v_pk_add_f32 v[38:39], v[38:39], v[42:43]
	s_waitcnt vmcnt(0)
	v_pk_add_f32 v[42:43], v[36:37], v[48:49]
	v_pk_add_f32 v[36:37], v[34:35], v[46:47]
	v_pk_add_f32 v[40:41], v[40:41], v[44:45]
	v_cvt_pk_bf16_f32 v34, v38, v39
	s_nop 0
	v_cvt_pk_bf16_f32 v35, v40, v41
	v_cvt_pk_bf16_f32 v36, v36, v37
	v_cvt_pk_bf16_f32 v37, v42, v43
	v_lshlrev_b32_e32 v254, 16, v34
	v_fmac_f32_e32 v253, v254, v254
	v_and_b32_e32 v254, 0xffff0000, v34
	v_fmac_f32_e32 v253, v254, v254
	v_lshlrev_b32_e32 v254, 16, v35
	v_fmac_f32_e32 v253, v254, v254
	v_and_b32_e32 v254, 0xffff0000, v35
	v_fmac_f32_e32 v253, v254, v254
	v_lshlrev_b32_e32 v254, 16, v36
	v_fmac_f32_e32 v253, v254, v254
	v_and_b32_e32 v254, 0xffff0000, v36
	v_fmac_f32_e32 v253, v254, v254
	v_lshlrev_b32_e32 v254, 16, v37
	v_fmac_f32_e32 v253, v254, v254
	v_and_b32_e32 v254, 0xffff0000, v37
	v_fmac_f32_e32 v253, v254, v254
	global_store_dwordx4 v[50:51], v[34:37], off offset:256
	global_store_dword v255, v253, s[100:101] offset:576
; __device__ __forceinline__ u32x4 pack8(const f32x4 a, const f32x4 b) { u32x4 w; w.x = cvt_pk_bf16(a[0], a[1]); w.y = cvt_pk_bf16(a[2], a[3]); w.z = cvt_pk_bf16(b[0], b[1]); w.w = cvt_pk_bf16(b[2], b[3]); return w; }
;     __device__ __forceinline__ void operator()(const f32x4 (&acc)[2][2][4][2], const Unit& u, int wr, int wc, int fr, int fq) const {
;         const int row0 = u.pm * BM + wr * 64 + fr, col0 = u.pn * BM + wc * 32 + 8 * fq;
; #pragma unroll
;         for (int ai = 0; ai < 2; ++ai)
; #pragma unroll
;             for (int m = 0; m < 4; ++m) { const int row = row0 + ai * HALF + m * 16; bf16_t* hp = Hx + (size_t)row * 1024;
;                 if (from_f32) { const float* xin = row < 16384 ? xa + (size_t)row * 1024 : xb + (size_t)(row - 16384) * 1024;
; #pragma unroll
;                     for (int bj = 0; bj < 2; ++bj) { const int c = col0 + bj * HALF; const f32x4 r0 = *(const f32x4*)(xin + c), r1 = *(const f32x4*)(xin + c + 4);
;                         *(u32x4*)(hp + c) = pack8(r0 + acc[ai][bj][m][0], r1 + acc[ai][bj][m][1]); }
;                 } else {
; #pragma unroll
;                     for (int bj = 0; bj < 2; ++bj) { const int c = col0 + bj * HALF; const u32x4 w = *(const u32x4*)(hp + c); f32x4 r0, r1;
;                         r0[0] = __uint_as_float(w.x << 16); r0[1] = __uint_as_float(w.x & 0xffff0000u); r0[2] = __uint_as_float(w.y << 16); r0[3] = __uint_as_float(w.y & 0xffff0000u);
;                         r1[0] = __uint_as_float(w.z << 16); r1[1] = __uint_as_float(w.z & 0xffff0000u); r1[2] = __uint_as_float(w.w << 16); r1[3] = __uint_as_float(w.w & 0xffff0000u);
;                         *(u32x4*)(hp + c) = pack8(r0 + acc[ai][bj][m][0], r1 + acc[ai][bj][m][1]); }
;                 }
;                 if (m & 1) asm volatile("" ::: "memory"); }
.LBB0_109:
	s_nop 1
	v_add_u32_e32 v36, 0xa0, v144
	v_ashrrev_i32_e32 v37, 31, v36
	v_lshlrev_b64 v[34:35], 11, v[36:37]
	v_lshl_add_u64 v[34:35], s[60:61], 0, v[34:35]
	s_and_b64 vcc, exec, s[8:9]
	s_mov_b64 s[4:5], -1
	s_cbranch_vccnz .LBB0_111
	v_lshl_add_u64 v[46:47], v[142:143], 1, v[34:35]
	global_load_dwordx4 v[38:41], v[46:47], off
	s_mov_b64 s[4:5], 0
	s_waitcnt vmcnt(0)
	v_lshlrev_b32_e32 v42, 16, v38
	v_and_b32_e32 v43, 0xffff0000, v38
	v_lshlrev_b32_e32 v38, 16, v39
	v_and_b32_e32 v39, 0xffff0000, v39
	v_lshlrev_b32_e32 v44, 16, v40
	v_and_b32_e32 v45, 0xffff0000, v40
	v_lshlrev_b32_e32 v40, 16, v41
	v_and_b32_e32 v41, 0xffff0000, v41
	v_pk_add_f32 v[48:49], v[32:33], v[38:39]
	v_pk_add_f32 v[38:39], v[30:31], v[42:43]
	v_pk_add_f32 v[42:43], v[28:29], v[40:41]
	v_pk_add_f32 v[40:41], v[26:27], v[44:45]
	v_cvt_pk_bf16_f32 v38, v38, v39
	v_cvt_pk_bf16_f32 v39, v48, v49
	s_nop 0
	v_cvt_pk_bf16_f32 v40, v40, v41
	v_cvt_pk_bf16_f32 v41, v42, v43
	global_load_dwordx4 v[42:45], v[46:47], off offset:256
	s_nop 0
	v_lshlrev_b32_e32 v254, 16, v38
	v_mul_f32_e32 v253, v254, v254
	v_and_b32_e32 v254, 0xffff0000, v38
	v_fmac_f32_e32 v253, v254, v254
	v_lshlrev_b32_e32 v254, 16, v39
	v_fmac_f32_e32 v253, v254, v254
	v_and_b32_e32 v254, 0xffff0000, v39
	v_fmac_f32_e32 v253, v254, v254
	v_lshlrev_b32_e32 v254, 16, v40
	v_fmac_f32_e32 v253, v254, v254
	v_and_b32_e32 v254, 0xffff0000, v40
	v_fmac_f32_e32 v253, v254, v254
	v_lshlrev_b32_e32 v254, 16, v41
	v_fmac_f32_e32 v253, v254, v254
	v_and_b32_e32 v254, 0xffff0000, v41
	v_fmac_f32_e32 v253, v254, v254
	global_store_dwordx4 v[46:47], v[38:41], off
	s_waitcnt vmcnt(1)
	s_nop 0
	v_lshlrev_b32_e32 v38, 16, v42
	v_and_b32_e32 v39, 0xffff0000, v42
	v_lshlrev_b32_e32 v40, 16, v43
	v_and_b32_e32 v41, 0xffff0000, v43
	v_lshlrev_b32_e32 v42, 16, v44
	v_and_b32_e32 v43, 0xffff0000, v44
	v_lshlrev_b32_e32 v44, 16, v45
	v_and_b32_e32 v45, 0xffff0000, v45
	v_pk_add_f32 v[40:41], v[24:25], v[40:41]
	v_pk_add_f32 v[38:39], v[22:23], v[38:39]
	v_pk_add_f32 v[44:45], v[20:21], v[44:45]
	v_pk_add_f32 v[42:43], v[18:19], v[42:43]
	v_cvt_pk_bf16_f32 v38, v38, v39
	v_cvt_pk_bf16_f32 v39, v40, v41
	s_nop 0
	v_cvt_pk_bf16_f32 v40, v42, v43
	v_cvt_pk_bf16_f32 v41, v44, v45
	v_lshlrev_b32_e32 v254, 16, v38
	v_fmac_f32_e32 v253, v254, v254
	v_and_b32_e32 v254, 0xffff0000, v38
	v_fmac_f32_e32 v253, v254, v254
	v_lshlrev_b32_e32 v254, 16, v39
	v_fmac_f32_e32 v253, v254, v254
	v_and_b32_e32 v254, 0xffff0000, v39
	v_fmac_f32_e32 v253, v254, v254
	v_lshlrev_b32_e32 v254, 16, v40
	v_fmac_f32_e32 v253, v254, v254
	v_and_b32_e32 v254, 0xffff0000, v40
	v_fmac_f32_e32 v253, v254, v254
	v_lshlrev_b32_e32 v254, 16, v41
	v_fmac_f32_e32 v253, v254, v254
	v_and_b32_e32 v254, 0xffff0000, v41
	v_fmac_f32_e32 v253, v254, v254
	global_store_dwordx4 v[46:47], v[38:41], off offset:256
	global_store_dword v255, v253, s[100:101] offset:640
.LBB0_111:
	s_andn2_b64 vcc, exec, s[4:5]
	s_cbranch_vccnz .LBB0_113
	v_add_u32_e32 v0, 0xffffc0a0, v144
	v_lshlrev_b64 v[36:37], 10, v[36:37]
	v_lshlrev_b64 v[38:39], 12, v[0:1]
	s_movk_i32 s0, 0x3f60
	v_lshl_add_u64 v[36:37], v[36:37], 2, s[20:21]
	v_lshl_add_u64 v[38:39], s[22:23], 0, v[38:39]
	v_cmp_gt_i32_e32 vcc, s0, v144
	v_lshl_add_u64 v[34:35], v[142:143], 1, v[34:35]
	s_nop 0
	v_cndmask_b32_e32 v37, v39, v37, vcc
	v_cndmask_b32_e32 v36, v38, v36, vcc
	v_lshl_add_u64 v[44:45], v[142:143], 2, v[36:37]
	global_load_dwordx4 v[36:39], v[44:45], off
	global_load_dwordx4 v[40:43], v[44:45], off offset:16
	s_waitcnt vmcnt(0)
	v_pk_add_f32 v[30:31], v[30:31], v[36:37]
	v_pk_add_f32 v[36:37], v[28:29], v[42:43]
	v_pk_add_f32 v[28:29], v[26:27], v[40:41]
	v_pk_add_f32 v[32:33], v[32:33], v[38:39]
	v_cvt_pk_bf16_f32 v26, v30, v31
	s_nop 0
	v_cvt_pk_bf16_f32 v27, v32, v33
	v_cvt_pk_bf16_f32 v28, v28, v29
	v_cvt_pk_bf16_f32 v29, v36, v37
	v_lshlrev_b32_e32 v254, 16, v26
	v_mul_f32_e32 v253, v254, v254
	v_and_b32_e32 v254, 0xffff0000, v26
	v_fmac_f32_e32 v253, v254, v254
	v_lshlrev_b32_e32 v254, 16, v27
	v_fmac_f32_e32 v253, v254, v254
	v_and_b32_e32 v254, 0xffff0000, v27
	v_fmac_f32_e32 v253, v254, v254
	v_lshlrev_b32_e32 v254, 16, v28
	v_fmac_f32_e32 v253, v254, v254
	v_and_b32_e32 v254, 0xffff0000, v28
	v_fmac_f32_e32 v253, v254, v254
	v_lshlrev_b32_e32 v254, 16, v29
	v_fmac_f32_e32 v253, v254, v254
	v_and_b32_e32 v254, 0xffff0000, v29
	v_fmac_f32_e32 v253, v254, v254
	global_store_dwordx4 v[34:35], v[26:29], off
	global_load_dwordx4 v[26:29], v[44:45], off offset:512
	s_nop 0
	global_load_dwordx4 v[30:33], v[44:45], off offset:528
	s_waitcnt vmcnt(1)
	v_pk_add_f32 v[22:23], v[22:23], v[26:27]
	s_waitcnt vmcnt(0)
	v_pk_add_f32 v[26:27], v[20:21], v[32:33]
	v_pk_add_f32 v[20:21], v[18:19], v[30:31]
	v_pk_add_f32 v[24:25], v[24:25], v[28:29]
	v_cvt_pk_bf16_f32 v18, v22, v23
	s_nop 0
	v_cvt_pk_bf16_f32 v19, v24, v25
	v_cvt_pk_bf16_f32 v20, v20, v21
	v_cvt_pk_bf16_f32 v21, v26, v27
	v_lshlrev_b32_e32 v254, 16, v18
	v_fmac_f32_e32 v253, v254, v254
	v_and_b32_e32 v254, 0xffff0000, v18
	v_fmac_f32_e32 v253, v254, v254
	v_lshlrev_b32_e32 v254, 16, v19
	v_fmac_f32_e32 v253, v254, v254
	v_and_b32_e32 v254, 0xffff0000, v19
	v_fmac_f32_e32 v253, v254, v254
	v_lshlrev_b32_e32 v254, 16, v20
	v_fmac_f32_e32 v253, v254, v254
	v_and_b32_e32 v254, 0xffff0000, v20
	v_fmac_f32_e32 v253, v254, v254
	v_lshlrev_b32_e32 v254, 16, v21
	v_fmac_f32_e32 v253, v254, v254
	v_and_b32_e32 v254, 0xffff0000, v21
	v_fmac_f32_e32 v253, v254, v254
	global_store_dwordx4 v[34:35], v[18:21], off offset:256
	global_store_dword v255, v253, s[100:101] offset:640
; __device__ __forceinline__ u32x4 pack8(const f32x4 a, const f32x4 b) { u32x4 w; w.x = cvt_pk_bf16(a[0], a[1]); w.y = cvt_pk_bf16(a[2], a[3]); w.z = cvt_pk_bf16(b[0], b[1]); w.w = cvt_pk_bf16(b[2], b[3]); return w; }
;     __device__ __forceinline__ void operator()(const f32x4 (&acc)[2][2][4][2], const Unit& u, int wr, int wc, int fr, int fq) const {
;         const int row0 = u.pm * BM + wr * 64 + fr, col0 = u.pn * BM + wc * 32 + 8 * fq;
; #pragma unroll
;         for (int ai = 0; ai < 2; ++ai)
; #pragma unroll
;             for (int m = 0; m < 4; ++m) { const int row = row0 + ai * HALF + m * 16; bf16_t* hp = Hx + (size_t)row * 1024;
;                 if (from_f32) { const float* xin = row < 16384 ? xa + (size_t)row * 1024 : xb + (size_t)(row - 16384) * 1024;
; #pragma unroll
;                     for (int bj = 0; bj < 2; ++bj) { const int c = col0 + bj * HALF; const f32x4 r0 = *(const f32x4*)(xin + c), r1 = *(const f32x4*)(xin + c + 4);
;                         *(u32x4*)(hp + c) = pack8(r0 + acc[ai][bj][m][0], r1 + acc[ai][bj][m][1]); }
;                 } else {
; #pragma unroll
;                     for (int bj = 0; bj < 2; ++bj) { const int c = col0 + bj * HALF; const u32x4 w = *(const u32x4*)(hp + c); f32x4 r0, r1;
;                         r0[0] = __uint_as_float(w.x << 16); r0[1] = __uint_as_float(w.x & 0xffff0000u); r0[2] = __uint_as_float(w.y << 16); r0[3] = __uint_as_float(w.y & 0xffff0000u);
;                         r1[0] = __uint_as_float(w.z << 16); r1[1] = __uint_as_float(w.z & 0xffff0000u); r1[2] = __uint_as_float(w.w << 16); r1[3] = __uint_as_float(w.w & 0xffff0000u);
;                         *(u32x4*)(hp + c) = pack8(r0 + acc[ai][bj][m][0], r1 + acc[ai][bj][m][1]); }
;                 }
;                 if (m & 1) asm volatile("" ::: "memory"); }
.LBB0_113:
	s_nop 1
	v_add_u32_e32 v20, 0xb0, v144
	v_ashrrev_i32_e32 v21, 31, v20
	v_lshlrev_b64 v[18:19], 11, v[20:21]
	v_lshl_add_u64 v[18:19], s[60:61], 0, v[18:19]
	s_and_b64 vcc, exec, s[8:9]
	s_mov_b64 s[4:5], -1
	s_cbranch_vccnz .LBB0_115
	v_lshl_add_u64 v[30:31], v[142:143], 1, v[18:19]
	global_load_dwordx4 v[22:25], v[30:31], off
	s_mov_b64 s[4:5], 0
	s_waitcnt vmcnt(0)
	v_lshlrev_b32_e32 v26, 16, v22
	v_and_b32_e32 v27, 0xffff0000, v22
	v_lshlrev_b32_e32 v22, 16, v23
	v_and_b32_e32 v23, 0xffff0000, v23
	v_lshlrev_b32_e32 v28, 16, v24
	v_and_b32_e32 v29, 0xffff0000, v24
	v_lshlrev_b32_e32 v24, 16, v25
	v_and_b32_e32 v25, 0xffff0000, v25
	v_pk_add_f32 v[32:33], v[16:17], v[22:23]
	v_pk_add_f32 v[22:23], v[14:15], v[26:27]
	v_pk_add_f32 v[26:27], v[12:13], v[24:25]
	v_pk_add_f32 v[24:25], v[10:11], v[28:29]
	v_cvt_pk_bf16_f32 v22, v22, v23
	v_cvt_pk_bf16_f32 v23, v32, v33
	s_nop 0
	v_cvt_pk_bf16_f32 v24, v24, v25
	v_cvt_pk_bf16_f32 v25, v26, v27
	global_load_dwordx4 v[26:29], v[30:31], off offset:256
	s_nop 0
	v_lshlrev_b32_e32 v254, 16, v22
	v_mul_f32_e32 v253, v254, v254
	v_and_b32_e32 v254, 0xffff0000, v22
	v_fmac_f32_e32 v253, v254, v254
	v_lshlrev_b32_e32 v254, 16, v23
	v_fmac_f32_e32 v253, v254, v254
	v_and_b32_e32 v254, 0xffff0000, v23
	v_fmac_f32_e32 v253, v254, v254
	v_lshlrev_b32_e32 v254, 16, v24
	v_fmac_f32_e32 v253, v254, v254
	v_and_b32_e32 v254, 0xffff0000, v24
	v_fmac_f32_e32 v253, v254, v254
	v_lshlrev_b32_e32 v254, 16, v25
	v_fmac_f32_e32 v253, v254, v254
	v_and_b32_e32 v254, 0xffff0000, v25
	v_fmac_f32_e32 v253, v254, v254
	global_store_dwordx4 v[30:31], v[22:25], off
	s_waitcnt vmcnt(1)
	s_nop 0
	v_lshlrev_b32_e32 v22, 16, v26
	v_and_b32_e32 v23, 0xffff0000, v26
	v_lshlrev_b32_e32 v24, 16, v27
	v_and_b32_e32 v25, 0xffff0000, v27
	v_lshlrev_b32_e32 v26, 16, v28
	v_and_b32_e32 v27, 0xffff0000, v28
	v_lshlrev_b32_e32 v28, 16, v29
	v_and_b32_e32 v29, 0xffff0000, v29
	v_pk_add_f32 v[24:25], v[8:9], v[24:25]
	v_pk_add_f32 v[22:23], v[6:7], v[22:23]
	v_pk_add_f32 v[28:29], v[4:5], v[28:29]
	v_pk_add_f32 v[26:27], v[2:3], v[26:27]
	v_cvt_pk_bf16_f32 v22, v22, v23
	v_cvt_pk_bf16_f32 v23, v24, v25
	s_nop 0
	v_cvt_pk_bf16_f32 v24, v26, v27
	v_cvt_pk_bf16_f32 v25, v28, v29
	v_lshlrev_b32_e32 v254, 16, v22
	v_fmac_f32_e32 v253, v254, v254
	v_and_b32_e32 v254, 0xffff0000, v22
	v_fmac_f32_e32 v253, v254, v254
	v_lshlrev_b32_e32 v254, 16, v23
	v_fmac_f32_e32 v253, v254, v254
	v_and_b32_e32 v254, 0xffff0000, v23
	v_fmac_f32_e32 v253, v254, v254
	v_lshlrev_b32_e32 v254, 16, v24
	v_fmac_f32_e32 v253, v254, v254
	v_and_b32_e32 v254, 0xffff0000, v24
	v_fmac_f32_e32 v253, v254, v254
	v_lshlrev_b32_e32 v254, 16, v25
	v_fmac_f32_e32 v253, v254, v254
	v_and_b32_e32 v254, 0xffff0000, v25
	v_fmac_f32_e32 v253, v254, v254
	global_store_dwordx4 v[30:31], v[22:25], off offset:256
	global_store_dword v255, v253, s[100:101] offset:704
.LBB0_115:
	s_andn2_b64 vcc, exec, s[4:5]
	s_cbranch_vccnz .LBB0_117
	v_add_u32_e32 v0, 0xffffc0b0, v144
	v_lshlrev_b64 v[20:21], 10, v[20:21]
	v_lshlrev_b64 v[22:23], 12, v[0:1]
	s_movk_i32 s0, 0x3f50
	v_lshl_add_u64 v[20:21], v[20:21], 2, s[20:21]
	v_lshl_add_u64 v[22:23], s[22:23], 0, v[22:23]
	v_cmp_gt_i32_e32 vcc, s0, v144
	v_lshl_add_u64 v[18:19], v[142:143], 1, v[18:19]
	s_nop 0
	v_cndmask_b32_e32 v21, v23, v21, vcc
	v_cndmask_b32_e32 v20, v22, v20, vcc
	v_lshl_add_u64 v[28:29], v[142:143], 2, v[20:21]
	global_load_dwordx4 v[20:23], v[28:29], off
	global_load_dwordx4 v[24:27], v[28:29], off offset:16
	s_waitcnt vmcnt(0)
	v_pk_add_f32 v[14:15], v[14:15], v[20:21]
	v_pk_add_f32 v[20:21], v[12:13], v[26:27]
	v_pk_add_f32 v[12:13], v[10:11], v[24:25]
	v_pk_add_f32 v[16:17], v[16:17], v[22:23]
	v_cvt_pk_bf16_f32 v10, v14, v15
	s_nop 0
	v_cvt_pk_bf16_f32 v11, v16, v17
	v_cvt_pk_bf16_f32 v12, v12, v13
	v_cvt_pk_bf16_f32 v13, v20, v21
	v_lshlrev_b32_e32 v254, 16, v10
	v_mul_f32_e32 v253, v254, v254
	v_and_b32_e32 v254, 0xffff0000, v10
	v_fmac_f32_e32 v253, v254, v254
	v_lshlrev_b32_e32 v254, 16, v11
	v_fmac_f32_e32 v253, v254, v254
	v_and_b32_e32 v254, 0xffff0000, v11
	v_fmac_f32_e32 v253, v254, v254
	v_lshlrev_b32_e32 v254, 16, v12
	v_fmac_f32_e32 v253, v254, v254
	v_and_b32_e32 v254, 0xffff0000, v12
	v_fmac_f32_e32 v253, v254, v254
	v_lshlrev_b32_e32 v254, 16, v13
	v_fmac_f32_e32 v253, v254, v254
	v_and_b32_e32 v254, 0xffff0000, v13
	v_fmac_f32_e32 v253, v254, v254
	global_store_dwordx4 v[18:19], v[10:13], off
	global_load_dwordx4 v[10:13], v[28:29], off offset:512
	s_nop 0
	global_load_dwordx4 v[14:17], v[28:29], off offset:528
	s_waitcnt vmcnt(1)
	v_pk_add_f32 v[6:7], v[6:7], v[10:11]
	s_waitcnt vmcnt(0)
	v_pk_add_f32 v[10:11], v[4:5], v[16:17]
	v_pk_add_f32 v[4:5], v[2:3], v[14:15]
	v_pk_add_f32 v[8:9], v[8:9], v[12:13]
	v_cvt_pk_bf16_f32 v2, v6, v7
	s_nop 0
	v_cvt_pk_bf16_f32 v3, v8, v9
	v_cvt_pk_bf16_f32 v4, v4, v5
	v_cvt_pk_bf16_f32 v5, v10, v11
	v_lshlrev_b32_e32 v254, 16, v2
	v_fmac_f32_e32 v253, v254, v254
	v_and_b32_e32 v254, 0xffff0000, v2
	v_fmac_f32_e32 v253, v254, v254
	v_lshlrev_b32_e32 v254, 16, v3
	v_fmac_f32_e32 v253, v254, v254
	v_and_b32_e32 v254, 0xffff0000, v3
	v_fmac_f32_e32 v253, v254, v254
	v_lshlrev_b32_e32 v254, 16, v4
	v_fmac_f32_e32 v253, v254, v254
	v_and_b32_e32 v254, 0xffff0000, v4
	v_fmac_f32_e32 v253, v254, v254
	v_lshlrev_b32_e32 v254, 16, v5
	v_fmac_f32_e32 v253, v254, v254
	v_and_b32_e32 v254, 0xffff0000, v5
	v_fmac_f32_e32 v253, v254, v254
	global_store_dwordx4 v[18:19], v[2:5], off offset:256
	global_store_dword v255, v253, s[100:101] offset:704

; __device__ __forceinline__ void rstd_rows(const bf16_t* __restrict__ Hb, float* __restrict__ rs, int nrows, int gw, int NGW, int lane) {
;     for (int m = gw; m < nrows; m += 2 * NGW) {
;         const int m2 = m + NGW; const bool has2 = m2 < nrows;
;         const u32x4* p0 = (const u32x4*)(Hb + (size_t)m * DMODEL) + lane; const u32x4* p1 = (const u32x4*)(Hb + (size_t)(has2 ? m2 : m) * DMODEL) + lane;
;         const u32x4 a0 = p0[0], a1 = p0[64], b0 = p1[0], b1 = p1[64];
;         float s0 = 0.f, s1 = 0.f;
; #pragma unroll
;         for (int k = 0; k < 4; ++k) { float x, y;
;             x = __uint_as_float(a0[k] << 16); y = __uint_as_float(a0[k] & 0xffff0000u); s0 += x * x + y * y;
;             x = __uint_as_float(a1[k] << 16); y = __uint_as_float(a1[k] & 0xffff0000u); s0 += x * x + y * y;
;             x = __uint_as_float(b0[k] << 16); y = __uint_as_float(b0[k] & 0xffff0000u); s1 += x * x + y * y;
;             x = __uint_as_float(b1[k] << 16); y = __uint_as_float(b1[k] & 0xffff0000u); s1 += x * x + y * y; }
;         s0 = wave_sum(s0); s1 = wave_sum(s1);
;         if (lane == 0) { rs[m] = rsqrtf(s0 * (1.0f / DMODEL) + EPS); if (has2) rs[m2] = rsqrtf(s1 * (1.0f / DMODEL) + EPS); }
;     }
; }
.LBB0_388:
	s_nop 0
	v_readlane_b32 s4, v252, 34
	v_readlane_b32 s5, v252, 35
	v_readlane_b32 s34, v252, 11
	v_readlane_b32 s38, v252, 29
	s_andn2_b64 vcc, exec, s[4:5]
	v_readlane_b32 s35, v252, 12
	v_readlane_b32 s39, v252, 30
	v_readlane_b32 s57, v252, 10
	s_cbranch_vccnz .LBB0_396
	s_cmp_eq_u32 s59, 0
	s_cselect_b64 s[4:5], -1, 0
	s_cmp_lt_i32 s38, 14
	s_cselect_b64 s[6:7], -1, 0
	v_mbcnt_lo_u32_b32 v0, -1, 0
	v_mbcnt_hi_u32_b32 v0, -1, v0
	s_and_b64 s[4:5], s[6:7], s[4:5]
	v_add_u32_e32 v0, s33, v0
	s_and_b64 vcc, exec, s[4:5]
	s_cbranch_vccnz .LBB0_396
	s_lshl_b32 s0, s62, 3
	s_add_i32 s8, s0, s57
	s_cmp_gt_i32 s8, 0x13fff
	s_cbranch_scc1 .LBB0_396
	v_readlane_b32 s4, v252, 21
	v_readlane_b32 s6, v252, 23
	v_readlane_b32 s7, v252, 24
	s_add_u32 s0, s6, 0x300000
	v_and_b32_e32 v4, 63, v0
	v_readlane_b32 s5, v252, 22
	s_addc_u32 s13, s7, 0
	v_lshlrev_b32_e32 v0, 4, v4
	s_ashr_i32 s55, s54, 31
	v_lshl_add_u64 v[2:3], s[60:61], 0, v[0:1]
	s_lshl_b32 s10, s8, 6
	v_add_u32_e32 v4, s10, v4
	s_lshl_b32 s10, s54, 6
	s_add_u32 s100, s6, 0x36600000
	s_addc_u32 s101, s7, 0
	s_mov_b32 s16, s0
	s_mov_b32 s17, s13
.Lrsl_loop:
	v_cmp_gt_u32_e32 vcc, 0x14000, v4
	s_and_saveexec_b64 s[14:15], vcc
	s_cbranch_execz .Lrsl_done
	v_lshlrev_b32_e32 v5, 2, v4
	s_mov_b64 s[18:19], s[100:101]
	global_load_dword v8, v5, s[18:19]
	s_add_u32 s18, s18, 0x50000
	s_addc_u32 s19, s19, 0
	global_load_dword v9, v5, s[18:19]
	s_add_u32 s18, s18, 0x50000
	s_addc_u32 s19, s19, 0
	global_load_dword v10, v5, s[18:19]
	s_add_u32 s18, s18, 0x50000
	s_addc_u32 s19, s19, 0
	global_load_dword v11, v5, s[18:19]
	s_add_u32 s18, s18, 0x50000
	s_addc_u32 s19, s19, 0
	global_load_dword v12, v5, s[18:19]
	s_add_u32 s18, s18, 0x50000
	s_addc_u32 s19, s19, 0
	global_load_dword v13, v5, s[18:19]
	s_add_u32 s18, s18, 0x50000
	s_addc_u32 s19, s19, 0
	global_load_dword v14, v5, s[18:19]
	s_add_u32 s18, s18, 0x50000
	s_addc_u32 s19, s19, 0
	global_load_dword v15, v5, s[18:19]
	s_add_u32 s18, s18, 0x50000
	s_addc_u32 s19, s19, 0
	global_load_dword v16, v5, s[18:19]
	s_add_u32 s18, s18, 0x50000
	s_addc_u32 s19, s19, 0
	global_load_dword v17, v5, s[18:19]
	s_add_u32 s18, s18, 0x50000
	s_addc_u32 s19, s19, 0
	global_load_dword v18, v5, s[18:19]
	s_add_u32 s18, s18, 0x50000
	s_addc_u32 s19, s19, 0
	global_load_dword v19, v5, s[18:19]
	s_add_u32 s18, s18, 0x50000
	s_addc_u32 s19, s19, 0
	global_load_dword v20, v5, s[18:19]
	s_add_u32 s18, s18, 0x50000
	s_addc_u32 s19, s19, 0
	global_load_dword v21, v5, s[18:19]
	s_add_u32 s18, s18, 0x50000
	s_addc_u32 s19, s19, 0
	global_load_dword v22, v5, s[18:19]
	s_add_u32 s18, s18, 0x50000
	s_addc_u32 s19, s19, 0
	global_load_dword v23, v5, s[18:19]
	s_add_u32 s18, s18, 0x50000
	s_addc_u32 s19, s19, 0
	global_load_dword v24, v5, s[18:19]
	s_add_u32 s18, s18, 0x50000
	s_addc_u32 s19, s19, 0
	global_load_dword v25, v5, s[18:19]
	s_add_u32 s18, s18, 0x50000
	s_addc_u32 s19, s19, 0
	global_load_dword v26, v5, s[18:19]
	s_add_u32 s18, s18, 0x50000
	s_addc_u32 s19, s19, 0
	global_load_dword v27, v5, s[18:19]
	s_add_u32 s18, s18, 0x50000
	s_addc_u32 s19, s19, 0
	global_load_dword v28, v5, s[18:19]
	s_add_u32 s18, s18, 0x50000
	s_addc_u32 s19, s19, 0
	global_load_dword v29, v5, s[18:19]
	s_add_u32 s18, s18, 0x50000
	s_addc_u32 s19, s19, 0
	global_load_dword v30, v5, s[18:19]
	s_add_u32 s18, s18, 0x50000
	s_addc_u32 s19, s19, 0
	global_load_dword v31, v5, s[18:19]
	s_add_u32 s18, s18, 0x50000
	s_addc_u32 s19, s19, 0
	global_load_dword v32, v5, s[18:19]
	s_add_u32 s18, s18, 0x50000
	s_addc_u32 s19, s19, 0
	global_load_dword v33, v5, s[18:19]
	s_add_u32 s18, s18, 0x50000
	s_addc_u32 s19, s19, 0
	global_load_dword v34, v5, s[18:19]
	s_add_u32 s18, s18, 0x50000
	s_addc_u32 s19, s19, 0
	global_load_dword v35, v5, s[18:19]
	s_add_u32 s18, s18, 0x50000
	s_addc_u32 s19, s19, 0
	global_load_dword v36, v5, s[18:19]
	s_add_u32 s18, s18, 0x50000
	s_addc_u32 s19, s19, 0
	global_load_dword v37, v5, s[18:19]
	s_add_u32 s18, s18, 0x50000
	s_addc_u32 s19, s19, 0
	global_load_dword v38, v5, s[18:19]
	s_add_u32 s18, s18, 0x50000
	s_addc_u32 s19, s19, 0
	global_load_dword v39, v5, s[18:19]
	s_add_u32 s18, s18, 0x50000
	s_addc_u32 s19, s19, 0
	global_load_dword v40, v5, s[18:19]
	s_add_u32 s18, s18, 0x50000
	s_addc_u32 s19, s19, 0
	global_load_dword v41, v5, s[18:19]
	s_add_u32 s18, s18, 0x50000
	s_addc_u32 s19, s19, 0
	global_load_dword v42, v5, s[18:19]
	s_add_u32 s18, s18, 0x50000
	s_addc_u32 s19, s19, 0
	global_load_dword v43, v5, s[18:19]
	s_add_u32 s18, s18, 0x50000
	s_addc_u32 s19, s19, 0
	global_load_dword v44, v5, s[18:19]
	s_add_u32 s18, s18, 0x50000
	s_addc_u32 s19, s19, 0
	global_load_dword v45, v5, s[18:19]
	s_add_u32 s18, s18, 0x50000
	s_addc_u32 s19, s19, 0
	global_load_dword v46, v5, s[18:19]
	s_add_u32 s18, s18, 0x50000
	s_addc_u32 s19, s19, 0
	global_load_dword v47, v5, s[18:19]
	s_add_u32 s18, s18, 0x50000
	s_addc_u32 s19, s19, 0
	global_load_dword v48, v5, s[18:19]
	s_add_u32 s18, s18, 0x50000
	s_addc_u32 s19, s19, 0
	global_load_dword v49, v5, s[18:19]
	s_add_u32 s18, s18, 0x50000
	s_addc_u32 s19, s19, 0
	global_load_dword v50, v5, s[18:19]
	s_add_u32 s18, s18, 0x50000
	s_addc_u32 s19, s19, 0
	global_load_dword v51, v5, s[18:19]
	s_add_u32 s18, s18, 0x50000
	s_addc_u32 s19, s19, 0
	global_load_dword v52, v5, s[18:19]
	s_add_u32 s18, s18, 0x50000
	s_addc_u32 s19, s19, 0
	global_load_dword v53, v5, s[18:19]
	s_add_u32 s18, s18, 0x50000
	s_addc_u32 s19, s19, 0
	global_load_dword v54, v5, s[18:19]
	s_add_u32 s18, s18, 0x50000
	s_addc_u32 s19, s19, 0
	global_load_dword v55, v5, s[18:19]
	s_add_u32 s18, s18, 0x50000
	s_addc_u32 s19, s19, 0
	global_load_dword v56, v5, s[18:19]
	s_add_u32 s18, s18, 0x50000
	s_addc_u32 s19, s19, 0
	global_load_dword v57, v5, s[18:19]
	s_add_u32 s18, s18, 0x50000
	s_addc_u32 s19, s19, 0
	global_load_dword v58, v5, s[18:19]
	s_add_u32 s18, s18, 0x50000
	s_addc_u32 s19, s19, 0
	global_load_dword v59, v5, s[18:19]
	s_add_u32 s18, s18, 0x50000
	s_addc_u32 s19, s19, 0
	global_load_dword v60, v5, s[18:19]
	s_add_u32 s18, s18, 0x50000
	s_addc_u32 s19, s19, 0
	global_load_dword v61, v5, s[18:19]
	s_add_u32 s18, s18, 0x50000
	s_addc_u32 s19, s19, 0
	global_load_dword v62, v5, s[18:19]
	s_add_u32 s18, s18, 0x50000
	s_addc_u32 s19, s19, 0
	global_load_dword v63, v5, s[18:19]
	s_add_u32 s18, s18, 0x50000
	s_addc_u32 s19, s19, 0
	global_load_dword v64, v5, s[18:19]
	s_add_u32 s18, s18, 0x50000
	s_addc_u32 s19, s19, 0
	global_load_dword v65, v5, s[18:19]
	s_add_u32 s18, s18, 0x50000
	s_addc_u32 s19, s19, 0
	global_load_dword v66, v5, s[18:19]
	s_add_u32 s18, s18, 0x50000
	s_addc_u32 s19, s19, 0
	global_load_dword v67, v5, s[18:19]
	s_add_u32 s18, s18, 0x50000
	s_addc_u32 s19, s19, 0
	global_load_dword v68, v5, s[18:19]
	s_add_u32 s18, s18, 0x50000
	s_addc_u32 s19, s19, 0
	global_load_dword v69, v5, s[18:19]
	s_add_u32 s18, s18, 0x50000
	s_addc_u32 s19, s19, 0
	global_load_dword v70, v5, s[18:19]
	s_add_u32 s18, s18, 0x50000
	s_addc_u32 s19, s19, 0
	global_load_dword v71, v5, s[18:19]
	s_waitcnt vmcnt(55)
; __device__ __forceinline__ void rstd_rows(const bf16_t* __restrict__ Hb, float* __restrict__ rs, int nrows, int gw, int NGW, int lane) {
;     for (int m = gw; m < nrows; m += 2 * NGW) {
;         const int m2 = m + NGW; const bool has2 = m2 < nrows;
;         const u32x4* p0 = (const u32x4*)(Hb + (size_t)m * DMODEL) + lane; const u32x4* p1 = (const u32x4*)(Hb + (size_t)(has2 ? m2 : m) * DMODEL) + lane;
;         const u32x4 a0 = p0[0], a1 = p0[64], b0 = p1[0], b1 = p1[64];
;         float s0 = 0.f, s1 = 0.f;
; #pragma unroll
;         for (int k = 0; k < 4; ++k) { float x, y;
;             x = __uint_as_float(a0[k] << 16); y = __uint_as_float(a0[k] & 0xffff0000u); s0 += x * x + y * y;
;             x = __uint_as_float(a1[k] << 16); y = __uint_as_float(a1[k] & 0xffff0000u); s0 += x * x + y * y;
;             x = __uint_as_float(b0[k] << 16); y = __uint_as_float(b0[k] & 0xffff0000u); s1 += x * x + y * y;
;             x = __uint_as_float(b1[k] << 16); y = __uint_as_float(b1[k] & 0xffff0000u); s1 += x * x + y * y; }
;         s0 = wave_sum(s0); s1 = wave_sum(s1);
;         if (lane == 0) { rs[m] = rsqrtf(s0 * (1.0f / DMODEL) + EPS); if (has2) rs[m2] = rsqrtf(s1 * (1.0f / DMODEL) + EPS); }
;     }
; }
	v_add_f32_e32 v8, v8, v9
	v_add_f32_e32 v8, v8, v10
	v_add_f32_e32 v8, v8, v11
	v_add_f32_e32 v8, v8, v12
	v_add_f32_e32 v8, v8, v13
	v_add_f32_e32 v8, v8, v14
	v_add_f32_e32 v8, v8, v15
	v_add_f32_e32 v8, v8, v16
	s_waitcnt vmcnt(47)
	v_add_f32_e32 v8, v8, v17
	v_add_f32_e32 v8, v8, v18
	v_add_f32_e32 v8, v8, v19
	v_add_f32_e32 v8, v8, v20
	v_add_f32_e32 v8, v8, v21
	v_add_f32_e32 v8, v8, v22
	v_add_f32_e32 v8, v8, v23
	v_add_f32_e32 v8, v8, v24
	s_waitcnt vmcnt(39)
	v_add_f32_e32 v8, v8, v25
	v_add_f32_e32 v8, v8, v26
	v_add_f32_e32 v8, v8, v27
	v_add_f32_e32 v8, v8, v28
	v_add_f32_e32 v8, v8, v29
	v_add_f32_e32 v8, v8, v30
	v_add_f32_e32 v8, v8, v31
	v_add_f32_e32 v8, v8, v32
	s_waitcnt vmcnt(31)
	v_add_f32_e32 v8, v8, v33
	v_add_f32_e32 v8, v8, v34
	v_add_f32_e32 v8, v8, v35
	v_add_f32_e32 v8, v8, v36
	v_add_f32_e32 v8, v8, v37
	v_add_f32_e32 v8, v8, v38
	v_add_f32_e32 v8, v8, v39
	v_add_f32_e32 v8, v8, v40
	s_waitcnt vmcnt(23)
	v_add_f32_e32 v8, v8, v41
	v_add_f32_e32 v8, v8, v42
	v_add_f32_e32 v8, v8, v43
	v_add_f32_e32 v8, v8, v44
	v_add_f32_e32 v8, v8, v45
	v_add_f32_e32 v8, v8, v46
	v_add_f32_e32 v8, v8, v47
	v_add_f32_e32 v8, v8, v48
	s_waitcnt vmcnt(15)
	v_add_f32_e32 v8, v8, v49
	v_add_f32_e32 v8, v8, v50
	v_add_f32_e32 v8, v8, v51
	v_add_f32_e32 v8, v8, v52
	v_add_f32_e32 v8, v8, v53
	v_add_f32_e32 v8, v8, v54
	v_add_f32_e32 v8, v8, v55
	v_add_f32_e32 v8, v8, v56
	s_waitcnt vmcnt(7)
	v_add_f32_e32 v8, v8, v57
	v_add_f32_e32 v8, v8, v58
	v_add_f32_e32 v8, v8, v59
	v_add_f32_e32 v8, v8, v60
	v_add_f32_e32 v8, v8, v61
	v_add_f32_e32 v8, v8, v62
	v_add_f32_e32 v8, v8, v63
	v_add_f32_e32 v8, v8, v64
	s_waitcnt vmcnt(0)
	v_add_f32_e32 v8, v8, v65
	v_add_f32_e32 v8, v8, v66
	v_add_f32_e32 v8, v8, v67
	v_add_f32_e32 v8, v8, v68
	v_add_f32_e32 v8, v8, v69
	v_add_f32_e32 v8, v8, v70
	v_add_f32_e32 v8, v8, v71
	v_fmamk_f32 v8, v8, 0x3a800000, v200
	v_rsq_f32_e32 v8, v8
	s_nop 0
	global_store_dword v5, v8, s[16:17]
	s_or_b64 exec, exec, s[14:15]
	v_add_u32_e32 v4, s10, v4
	s_branch .Lrsl_loop
.Lrsl_done:
	s_or_b64 exec, exec, s[14:15]
.LBB0_396:
	s_mov_b64 s[4:5], 0

; __global__ void __launch_bounds__(512, 2) fwd_kernel(Args a) {
	.amdhsa_kernel _Z10fwd_kernel4Args
		.amdhsa_group_segment_fixed_size 0
		.amdhsa_private_segment_fixed_size 0
		.amdhsa_kernarg_size 496
		.amdhsa_user_sgpr_count 2
		.amdhsa_user_sgpr_dispatch_ptr 0
		.amdhsa_user_sgpr_queue_ptr 0
		.amdhsa_user_sgpr_kernarg_segment_ptr 1
		.amdhsa_user_sgpr_dispatch_id 0
		.amdhsa_user_sgpr_kernarg_preload_length 0
		.amdhsa_user_sgpr_kernarg_preload_offset 0
		.amdhsa_user_sgpr_private_segment_size 0
		.amdhsa_uses_dynamic_stack 0
		.amdhsa_enable_private_segment 0
		.amdhsa_system_sgpr_workgroup_id_x 1
		.amdhsa_system_sgpr_workgroup_id_y 0
		.amdhsa_system_sgpr_workgroup_id_z 0
		.amdhsa_system_sgpr_workgroup_info 0
		.amdhsa_system_vgpr_workitem_id 2
		.amdhsa_next_free_vgpr 256
		.amdhsa_next_free_sgpr 102
		.amdhsa_accum_offset 256
		.amdhsa_reserve_vcc 1
		.amdhsa_float_round_mode_32 0
		.amdhsa_float_round_mode_16_64 0
		.amdhsa_float_denorm_mode_32 3
		.amdhsa_float_denorm_mode_16_64 3
		.amdhsa_dx10_clamp 1
		.amdhsa_ieee_mode 1
		.amdhsa_fp16_overflow 0
		.amdhsa_tg_split 0
		.amdhsa_exception_fp_ieee_invalid_op 0
		.amdhsa_exception_fp_denorm_src 0
		.amdhsa_exception_fp_ieee_div_zero 0
		.amdhsa_exception_fp_ieee_overflow 0
		.amdhsa_exception_fp_ieee_underflow 0
		.amdhsa_exception_fp_ieee_inexact 0
		.amdhsa_exception_int_div_zero 0
	.end_amdhsa_kernel

; __global__ void __launch_bounds__(512, 2) fwd_kernel(Args a) {
amdhsa.kernels:
  - .agpr_count:     0
    .args:
      - .offset:         0
        .size:           240
        .value_kind:     by_value
      - .offset:         240
        .size:           4
        .value_kind:     hidden_block_count_x
      - .offset:         244
        .size:           4
        .value_kind:     hidden_block_count_y
      - .offset:         248
        .size:           4
        .value_kind:     hidden_block_count_z
      - .offset:         252
        .size:           2
        .value_kind:     hidden_group_size_x
      - .offset:         254
        .size:           2
        .value_kind:     hidden_group_size_y
      - .offset:         256
        .size:           2
        .value_kind:     hidden_group_size_z
      - .offset:         258
        .size:           2
        .value_kind:     hidden_remainder_x
      - .offset:         260
        .size:           2
        .value_kind:     hidden_remainder_y
      - .offset:         262
        .size:           2
        .value_kind:     hidden_remainder_z
      - .offset:         280
        .size:           8
        .value_kind:     hidden_global_offset_x
      - .offset:         288
        .size:           8
        .value_kind:     hidden_global_offset_y
      - .offset:         296
        .size:           8
        .value_kind:     hidden_global_offset_z
      - .offset:         304
        .size:           2
        .value_kind:     hidden_grid_dims
      - .offset:         328
        .size:           8
        .value_kind:     hidden_multigrid_sync_arg
      - .offset:         360
        .size:           4
        .value_kind:     hidden_dynamic_lds_size
    .group_segment_fixed_size: 0
    .kernarg_segment_align: 8
    .kernarg_segment_size: 496
    .language:       OpenCL C
    .language_version:
      - 2
      - 0
    .max_flat_workgroup_size: 512
    .name:           _Z10fwd_kernel4Args
    .private_segment_fixed_size: 0
    .sgpr_count:     108
    .sgpr_spill_count: 65
    .symbol:         _Z10fwd_kernel4Args.kd
    .uniform_work_group_size: 1
    .uses_dynamic_stack: false
    .vgpr_count:     256
    .vgpr_spill_count: 0
    .wavefront_size: 64
